# GEMM K-loops of P1/P4/P14: first K-iteration of every non-first tile peeled with its first two vmcnt waits widened by the count of epilogue stores in the in-order queue
# speedup vs baseline: 1.0001x; 1.0001x over previous
; #define PG8_STAGE(bufoff, gbase, voff) do { _Pragma("unroll") for (int _i = 0; _i < 2; ++_i) \
;         __builtin_amdgcn_global_load_lds((const unsigned*)((const char*)(gbase) + (voff)[_i]), (PG8_LAS unsigned*)(lds + (bufoff) + ldsw + _i * 8192), 16, 0, 0); } while (0)
; #define PG8_LDA(dst, b, h) do { _Pragma("unroll") for (int m = 0; m < 4; ++m) _Pragma("unroll") for (int k = 0; k < 2; ++k) dst[m][k] = *(const PG8_LAS bf16x8*)(lds + PG8_SA(b, h) + aoff + m * 2048 + k * 1024); } while (0)
; #define PG8_LDB(dst, b, h) do { _Pragma("unroll") for (int n = 0; n < 2; ++n) _Pragma("unroll") for (int k = 0; k < 2; ++k) dst[n][k] = *(const PG8_LAS bf16x8*)(lds + PG8_SB(b, h) + boff + n * 2048 + k * 1024); } while (0)
; #define PG8_MMA(ai, bj, At, Bt) do { __builtin_amdgcn_s_setprio(1); _Pragma("unroll") for (int m = 0; m < 4; ++m) _Pragma("unroll") for (int n = 0; n < 2; ++n) _Pragma("unroll") for (int k = 0; k < 2; ++k) \
;         acc[ai][bj][m][n] = __builtin_amdgcn_mfma_f32_16x16x32_bf16(Bt[n][k], At[m][k], acc[ai][bj][m][n], 0, 0, 0); __builtin_amdgcn_s_setprio(0); } while (0)
; #define PG8_WAIT_V(n) asm volatile("s_waitcnt vmcnt(" #n ")" ::: "memory")
; #define PG8_WAIT_L(n) asm volatile("s_waitcnt lgkmcnt(" #n ")" ::: "memory")
; #define PG8_BAR __builtin_amdgcn_s_barrier()
; #define PG8_SCHED __builtin_amdgcn_sched_barrier(0)
; template <class Epi, class Sched, bool ALIGN_EPI = false, bool SP2 = false>
; __device__ __forceinline__ void gemm_phase(PG8_LAS unsigned char* lds, const Gemm g, const Sched& S, const Epi& E) {
;     ...
;             PG8_LDB(B0, 0, 0); PG8_LDB(B1, 0, 1); PG8_SCHED; PG8_LDA(At, 0, 0); PG8_STAGE(PG8_SA(1, 1), a1 + hstep, voffA);
;             PG8_WAIT_V(8); PG8_WAIT_L(0); PG8_BAR; PG8_MMA(0, 0, At, B0); PG8_MMA(0, 1, At, B1); PG8_BAR; PG8_SCHED;
;     ...
;         for (int a = 0; a < 2; ++a)
; #pragma unroll
;             for (int b = 0; b < 2; ++b)
; #pragma unroll
;                 for (int m = 0; m < 4; ++m)
; #pragma unroll
;                     for (int n = 0; n < 2; ++n) acc[a][b][m][n] = (f32x4){0.f, 0.f, 0.f, 0.f};
;         cur = nxt; cA = nA; cB = nB; ++ui;
.LBB0_157:
	s_ashr_i32 s21, s20, 31
	s_lshl_b64 s[42:43], s[20:21], 20
	s_add_u32 s42, s28, s42
	s_addc_u32 s43, s29, s43
	s_and_b64 s[44:45], s[2:3], exec
	s_cselect_b32 s21, s43, s49
	s_cselect_b32 s73, s42, s48
	s_ashr_i32 s19, s18, 31
	s_lshl_b64 s[44:45], s[18:19], 20
	s_add_u32 s44, s31, s44
	s_addc_u32 s45, s35, s45
	s_and_b64 s[54:55], s[2:3], exec
	s_cselect_b32 s19, s45, s51
	s_cselect_b32 s74, s44, s50
	s_add_u32 s48, s48, 0x80080
	s_addc_u32 s49, s49, 0
	s_add_u32 s75, s50, 0x100
	v_mov_b32_e32 v0, 0
	s_addc_u32 s76, s51, 0
	s_mov_b32 s77, -2
	v_mov_b32_e32 v1, v0
	v_mov_b32_e32 v2, v0
	v_mov_b32_e32 v3, v0
	v_mov_b32_e32 v8, v0
	v_mov_b32_e32 v9, v0
	v_mov_b32_e32 v10, v0
	v_mov_b32_e32 v11, v0
	v_mov_b32_e32 v16, v0
	v_mov_b32_e32 v17, v0
	v_mov_b32_e32 v18, v0
	v_mov_b32_e32 v19, v0
	v_mov_b32_e32 v24, v0
	v_mov_b32_e32 v25, v0
	v_mov_b32_e32 v26, v0
	v_mov_b32_e32 v27, v0
	v_mov_b32_e32 v32, v0
	v_mov_b32_e32 v33, v0
	v_mov_b32_e32 v34, v0
	v_mov_b32_e32 v35, v0
	v_mov_b32_e32 v40, v0
	v_mov_b32_e32 v41, v0
	v_mov_b32_e32 v42, v0
	v_mov_b32_e32 v43, v0
	v_mov_b32_e32 v48, v0
	v_mov_b32_e32 v49, v0
	v_mov_b32_e32 v50, v0
	v_mov_b32_e32 v51, v0
	v_mov_b32_e32 v56, v0
	v_mov_b32_e32 v57, v0
	v_mov_b32_e32 v58, v0
	v_mov_b32_e32 v59, v0
	v_mov_b32_e32 v4, v0
	v_mov_b32_e32 v5, v0
	v_mov_b32_e32 v6, v0
	v_mov_b32_e32 v7, v0
	v_mov_b32_e32 v12, v0
	v_mov_b32_e32 v13, v0
	v_mov_b32_e32 v14, v0
	v_mov_b32_e32 v15, v0
	v_mov_b32_e32 v20, v0
	v_mov_b32_e32 v21, v0
	v_mov_b32_e32 v22, v0
	v_mov_b32_e32 v23, v0
	v_mov_b32_e32 v28, v0
	v_mov_b32_e32 v29, v0
	v_mov_b32_e32 v30, v0
	v_mov_b32_e32 v31, v0
	v_mov_b32_e32 v36, v0
	v_mov_b32_e32 v37, v0
	v_mov_b32_e32 v38, v0
	v_mov_b32_e32 v39, v0
	v_mov_b32_e32 v44, v0
	v_mov_b32_e32 v45, v0
	v_mov_b32_e32 v46, v0
	v_mov_b32_e32 v47, v0
	v_mov_b32_e32 v52, v0
	v_mov_b32_e32 v53, v0
	v_mov_b32_e32 v54, v0
	v_mov_b32_e32 v55, v0
	v_mov_b32_e32 v60, v0
	v_mov_b32_e32 v61, v0
	v_mov_b32_e32 v62, v0
	v_mov_b32_e32 v63, v0
	v_mov_b32_e32 v64, v0
	v_mov_b32_e32 v65, v0
	v_mov_b32_e32 v66, v0
	v_mov_b32_e32 v67, v0
	v_mov_b32_e32 v72, v0
	v_mov_b32_e32 v73, v0
	v_mov_b32_e32 v74, v0
	v_mov_b32_e32 v75, v0
	v_mov_b32_e32 v80, v0
	v_mov_b32_e32 v81, v0
	v_mov_b32_e32 v82, v0
	v_mov_b32_e32 v83, v0
	v_mov_b32_e32 v88, v0
	v_mov_b32_e32 v89, v0
	v_mov_b32_e32 v90, v0
	v_mov_b32_e32 v91, v0
	v_mov_b32_e32 v96, v0
	v_mov_b32_e32 v97, v0
	v_mov_b32_e32 v98, v0
	v_mov_b32_e32 v99, v0
	v_mov_b32_e32 v104, v0
	v_mov_b32_e32 v105, v0
	v_mov_b32_e32 v106, v0
	v_mov_b32_e32 v107, v0
	v_mov_b32_e32 v112, v0
	v_mov_b32_e32 v113, v0
	v_mov_b32_e32 v114, v0
	v_mov_b32_e32 v115, v0
	v_mov_b32_e32 v120, v0
	v_mov_b32_e32 v121, v0
	v_mov_b32_e32 v122, v0
	v_mov_b32_e32 v123, v0
	v_mov_b32_e32 v68, v0
	v_mov_b32_e32 v69, v0
	v_mov_b32_e32 v70, v0
	v_mov_b32_e32 v71, v0
	v_mov_b32_e32 v76, v0
	v_mov_b32_e32 v77, v0
	v_mov_b32_e32 v78, v0
	v_mov_b32_e32 v79, v0
	v_mov_b32_e32 v84, v0
	v_mov_b32_e32 v85, v0
	v_mov_b32_e32 v86, v0
	v_mov_b32_e32 v87, v0
	v_mov_b32_e32 v92, v0
	v_mov_b32_e32 v93, v0
	v_mov_b32_e32 v94, v0
	v_mov_b32_e32 v95, v0
	v_mov_b32_e32 v100, v0
	v_mov_b32_e32 v101, v0
	v_mov_b32_e32 v102, v0
	v_mov_b32_e32 v103, v0
	v_mov_b32_e32 v108, v0
	v_mov_b32_e32 v109, v0
	v_mov_b32_e32 v110, v0
	v_mov_b32_e32 v111, v0
	v_mov_b32_e32 v116, v0
	v_mov_b32_e32 v117, v0
	v_mov_b32_e32 v118, v0
	v_mov_b32_e32 v119, v0
	v_mov_b32_e32 v124, v0
	v_mov_b32_e32 v125, v0
	v_mov_b32_e32 v126, v0
	v_mov_b32_e32 v127, v0
	s_cmp_eq_u32 s62, 1
	s_cbranch_scc1 .LBB0_158
	ds_read_b128 v[144:147], v151
	ds_read_b128 v[154:157], v151 offset:1024
	ds_read_b128 v[158:161], v151 offset:2048
	ds_read_b128 v[162:165], v151 offset:3072
	ds_read_b128 v[166:169], v152
	ds_read_b128 v[170:173], v152 offset:1024
	ds_read_b128 v[174:177], v152 offset:2048
	ds_read_b128 v[178:181], v152 offset:3072
	s_add_u32 s50, s48, 0xfff80080
	s_addc_u32 s51, s49, -1
	s_cmp_eq_u32 s77, 28
	s_cselect_b32 s55, s21, s51
	s_cselect_b32 s54, s73, s50
	s_cselect_b32 s51, s19, s76
	s_cselect_b32 s50, s74, s75
	v_lshl_add_u64 v[214:215], s[48:49], 0, v[136:137]
	s_add_i32 m0, s47, 0xc000
	ds_read_b128 v[182:185], v153
	ds_read_b128 v[186:189], v153 offset:1024
	ds_read_b128 v[190:193], v153 offset:2048
	ds_read_b128 v[194:197], v153 offset:3072
	ds_read_b128 v[198:201], v153 offset:4096
	ds_read_b128 v[202:205], v153 offset:5120
	ds_read_b128 v[206:209], v153 offset:6144
	ds_read_b128 v[210:213], v153 offset:7168
	global_load_lds_dwordx4 v[214:215], off
	v_lshl_add_u64 v[214:215], s[48:49], 0, v[138:139]
	s_add_i32 m0, s47, 0xe000
	s_nop 0
	global_load_lds_dwordx4 v[214:215], off
	s_waitcnt vmcnt(16)
	s_waitcnt lgkmcnt(0)
	s_barrier
; #define PG8_STAGE(bufoff, gbase, voff) do { _Pragma("unroll") for (int _i = 0; _i < 2; ++_i) \
;         __builtin_amdgcn_global_load_lds((const unsigned*)((const char*)(gbase) + (voff)[_i]), (PG8_LAS unsigned*)(lds + (bufoff) + ldsw + _i * 8192), 16, 0, 0); } while (0)
; #define PG8_LDA(dst, b, h) do { _Pragma("unroll") for (int m = 0; m < 4; ++m) _Pragma("unroll") for (int k = 0; k < 2; ++k) dst[m][k] = *(const PG8_LAS bf16x8*)(lds + PG8_SA(b, h) + aoff + m * 2048 + k * 1024); } while (0)
; #define PG8_MMA(ai, bj, At, Bt) do { __builtin_amdgcn_s_setprio(1); _Pragma("unroll") for (int m = 0; m < 4; ++m) _Pragma("unroll") for (int n = 0; n < 2; ++n) _Pragma("unroll") for (int k = 0; k < 2; ++k) \
;         acc[ai][bj][m][n] = __builtin_amdgcn_mfma_f32_16x16x32_bf16(Bt[n][k], At[m][k], acc[ai][bj][m][n], 0, 0, 0); __builtin_amdgcn_s_setprio(0); } while (0)
; #define PG8_WAIT_V(n) asm volatile("s_waitcnt vmcnt(" #n ")" ::: "memory")
; #define PG8_WAIT_L(n) asm volatile("s_waitcnt lgkmcnt(" #n ")" ::: "memory")
; #define PG8_BAR __builtin_amdgcn_s_barrier()
; #define PG8_SCHED __builtin_amdgcn_sched_barrier(0)
; template <class Epi, class Sched, bool ALIGN_EPI = false, bool SP2 = false>
; __device__ __forceinline__ void gemm_phase(PG8_LAS unsigned char* lds, const Gemm g, const Sched& S, const Epi& E) {
;     ...
;             PG8_WAIT_V(8); PG8_WAIT_L(0); PG8_BAR; PG8_MMA(0, 0, At, B0); PG8_MMA(0, 1, At, B1); PG8_BAR; PG8_SCHED;
;             PG8_LDA(At, 0, 1); PG8_STAGE(PG8_SB(0, 0), b2, voffB); PG8_STAGE(PG8_SB(0, 1), b2 + hstep, voffB); PG8_STAGE(PG8_SA(0, 0), a2, voffA);
;             PG8_WAIT_V(8); PG8_WAIT_L(0); PG8_BAR; PG8_MMA(1, 0, At, B0); PG8_MMA(1, 1, At, B1); PG8_BAR; PG8_SCHED;
	s_setprio 1
	s_waitcnt lgkmcnt(0)
	v_mfma_f32_16x16x32_bf16 v[124:127], v[144:147], v[182:185], v[124:127]
	v_mfma_f32_16x16x32_bf16 v[116:119], v[158:161], v[182:185], v[116:119]
	v_mfma_f32_16x16x32_bf16 v[108:111], v[144:147], v[190:193], v[108:111]
	v_mfma_f32_16x16x32_bf16 v[100:103], v[158:161], v[190:193], v[100:103]
	v_mfma_f32_16x16x32_bf16 v[92:95], v[144:147], v[198:201], v[92:95]
	v_mfma_f32_16x16x32_bf16 v[84:87], v[158:161], v[198:201], v[84:87]
	v_mfma_f32_16x16x32_bf16 v[76:79], v[144:147], v[206:209], v[76:79]
	v_mfma_f32_16x16x32_bf16 v[68:71], v[158:161], v[206:209], v[68:71]
	v_mfma_f32_16x16x32_bf16 v[124:127], v[154:157], v[186:189], v[124:127]
	v_mfma_f32_16x16x32_bf16 v[116:119], v[162:165], v[186:189], v[116:119]
	v_mfma_f32_16x16x32_bf16 v[108:111], v[154:157], v[194:197], v[108:111]
	v_mfma_f32_16x16x32_bf16 v[100:103], v[162:165], v[194:197], v[100:103]
	v_mfma_f32_16x16x32_bf16 v[92:95], v[154:157], v[202:205], v[92:95]
	v_mfma_f32_16x16x32_bf16 v[84:87], v[162:165], v[202:205], v[84:87]
	v_mfma_f32_16x16x32_bf16 v[76:79], v[154:157], v[210:213], v[76:79]
	v_mfma_f32_16x16x32_bf16 v[68:71], v[162:165], v[210:213], v[68:71]
	s_setprio 0
	s_setprio 1
	v_mfma_f32_16x16x32_bf16 v[120:123], v[166:169], v[182:185], v[120:123]
	v_mfma_f32_16x16x32_bf16 v[112:115], v[174:177], v[182:185], v[112:115]
	v_mfma_f32_16x16x32_bf16 v[104:107], v[166:169], v[190:193], v[104:107]
	v_mfma_f32_16x16x32_bf16 v[96:99], v[174:177], v[190:193], v[96:99]
	v_mfma_f32_16x16x32_bf16 v[88:91], v[166:169], v[198:201], v[88:91]
	v_mfma_f32_16x16x32_bf16 v[80:83], v[174:177], v[198:201], v[80:83]
	v_mfma_f32_16x16x32_bf16 v[72:75], v[166:169], v[206:209], v[72:75]
	v_mfma_f32_16x16x32_bf16 v[64:67], v[174:177], v[206:209], v[64:67]
	v_mfma_f32_16x16x32_bf16 v[120:123], v[170:173], v[186:189], v[120:123]
	v_mfma_f32_16x16x32_bf16 v[112:115], v[178:181], v[186:189], v[112:115]
	v_mfma_f32_16x16x32_bf16 v[104:107], v[170:173], v[194:197], v[104:107]
	v_mfma_f32_16x16x32_bf16 v[96:99], v[178:181], v[194:197], v[96:99]
	v_mfma_f32_16x16x32_bf16 v[88:91], v[170:173], v[202:205], v[88:91]
	v_mfma_f32_16x16x32_bf16 v[80:83], v[178:181], v[202:205], v[80:83]
	v_mfma_f32_16x16x32_bf16 v[72:75], v[170:173], v[210:213], v[72:75]
	v_mfma_f32_16x16x32_bf16 v[64:67], v[178:181], v[210:213], v[64:67]
	s_setprio 0
	s_barrier
	s_add_i32 s78, s66, s56
	v_lshl_add_u64 v[214:215], s[50:51], 0, v[132:133]
	s_mov_b32 m0, s78
	ds_read_b128 v[182:185], v153 offset:16384
	ds_read_b128 v[186:189], v153 offset:17408
	ds_read_b128 v[190:193], v153 offset:18432
	ds_read_b128 v[194:197], v153 offset:19456
	ds_read_b128 v[198:201], v153 offset:20480
	ds_read_b128 v[202:205], v153 offset:21504
	ds_read_b128 v[206:209], v153 offset:22528
	ds_read_b128 v[210:213], v153 offset:23552
	global_load_lds_dwordx4 v[214:215], off
	s_add_i32 m0, s78, 0x2000
	s_add_u32 s78, s50, 0x80000
	v_lshl_add_u64 v[216:217], s[50:51], 0, v[128:129]
	s_addc_u32 s79, s51, 0
	s_add_i32 s80, s67, s56
	global_load_lds_dwordx4 v[216:217], off
	v_lshl_add_u64 v[220:221], s[78:79], 0, v[132:133]
	s_mov_b32 m0, s80
	v_lshl_add_u64 v[222:223], s[54:55], 0, v[130:131]
	global_load_lds_dwordx4 v[220:221], off
	v_lshl_add_u64 v[220:221], s[78:79], 0, v[128:129]
	s_add_i32 m0, s80, 0x2000
	s_nop 0
	global_load_lds_dwordx4 v[220:221], off
	v_lshl_add_u64 v[220:221], s[54:55], 0, v[134:135]
	s_mov_b32 m0, s47
	s_nop 0
	global_load_lds_dwordx4 v[220:221], off
	s_mov_b32 m0, s59
	s_nop 0
	global_load_lds_dwordx4 v[222:223], off
	s_waitcnt vmcnt(16)
	s_waitcnt lgkmcnt(0)
	s_barrier
	s_setprio 1
	s_waitcnt lgkmcnt(0)
	v_mfma_f32_16x16x32_bf16 v[60:63], v[144:147], v[182:185], v[60:63]
	v_mfma_f32_16x16x32_bf16 v[52:55], v[158:161], v[182:185], v[52:55]
	v_mfma_f32_16x16x32_bf16 v[44:47], v[144:147], v[190:193], v[44:47]
	v_mfma_f32_16x16x32_bf16 v[36:39], v[158:161], v[190:193], v[36:39]
	v_mfma_f32_16x16x32_bf16 v[28:31], v[144:147], v[198:201], v[28:31]
	v_mfma_f32_16x16x32_bf16 v[20:23], v[158:161], v[198:201], v[20:23]
	v_mfma_f32_16x16x32_bf16 v[12:15], v[144:147], v[206:209], v[12:15]
	v_mfma_f32_16x16x32_bf16 v[4:7], v[158:161], v[206:209], v[4:7]
	v_mfma_f32_16x16x32_bf16 v[60:63], v[154:157], v[186:189], v[60:63]
	v_mfma_f32_16x16x32_bf16 v[52:55], v[162:165], v[186:189], v[52:55]
	v_mfma_f32_16x16x32_bf16 v[44:47], v[154:157], v[194:197], v[44:47]
	v_mfma_f32_16x16x32_bf16 v[36:39], v[162:165], v[194:197], v[36:39]
	v_mfma_f32_16x16x32_bf16 v[28:31], v[154:157], v[202:205], v[28:31]
	v_mfma_f32_16x16x32_bf16 v[20:23], v[162:165], v[202:205], v[20:23]
	v_mfma_f32_16x16x32_bf16 v[12:15], v[154:157], v[210:213], v[12:15]
	v_mfma_f32_16x16x32_bf16 v[4:7], v[162:165], v[210:213], v[4:7]
	s_setprio 0
	s_setprio 1
	v_mfma_f32_16x16x32_bf16 v[56:59], v[166:169], v[182:185], v[56:59]
	v_mfma_f32_16x16x32_bf16 v[48:51], v[174:177], v[182:185], v[48:51]
	v_mfma_f32_16x16x32_bf16 v[40:43], v[166:169], v[190:193], v[40:43]
	v_mfma_f32_16x16x32_bf16 v[32:35], v[174:177], v[190:193], v[32:35]
	v_mfma_f32_16x16x32_bf16 v[24:27], v[166:169], v[198:201], v[24:27]
	v_mfma_f32_16x16x32_bf16 v[16:19], v[174:177], v[198:201], v[16:19]
	v_mfma_f32_16x16x32_bf16 v[8:11], v[166:169], v[206:209], v[8:11]
	v_mfma_f32_16x16x32_bf16 v[0:3], v[174:177], v[206:209], v[0:3]
	v_mfma_f32_16x16x32_bf16 v[56:59], v[170:173], v[186:189], v[56:59]
	v_mfma_f32_16x16x32_bf16 v[48:51], v[178:181], v[186:189], v[48:51]
	v_mfma_f32_16x16x32_bf16 v[40:43], v[170:173], v[194:197], v[40:43]
	v_mfma_f32_16x16x32_bf16 v[32:35], v[178:181], v[194:197], v[32:35]
	v_mfma_f32_16x16x32_bf16 v[24:27], v[170:173], v[202:205], v[24:27]
	v_mfma_f32_16x16x32_bf16 v[16:19], v[178:181], v[202:205], v[16:19]
	v_mfma_f32_16x16x32_bf16 v[8:11], v[170:173], v[210:213], v[8:11]
	v_mfma_f32_16x16x32_bf16 v[0:3], v[178:181], v[210:213], v[0:3]
	s_setprio 0
	s_barrier
; #define PG8_STAGE(bufoff, gbase, voff) do { _Pragma("unroll") for (int _i = 0; _i < 2; ++_i) \
;         __builtin_amdgcn_global_load_lds((const unsigned*)((const char*)(gbase) + (voff)[_i]), (PG8_LAS unsigned*)(lds + (bufoff) + ldsw + _i * 8192), 16, 0, 0); } while (0)
; #define PG8_LDA(dst, b, h) do { _Pragma("unroll") for (int m = 0; m < 4; ++m) _Pragma("unroll") for (int k = 0; k < 2; ++k) dst[m][k] = *(const PG8_LAS bf16x8*)(lds + PG8_SA(b, h) + aoff + m * 2048 + k * 1024); } while (0)
; #define PG8_LDB(dst, b, h) do { _Pragma("unroll") for (int n = 0; n < 2; ++n) _Pragma("unroll") for (int k = 0; k < 2; ++k) dst[n][k] = *(const PG8_LAS bf16x8*)(lds + PG8_SB(b, h) + boff + n * 2048 + k * 1024); } while (0)
; #define PG8_MMA(ai, bj, At, Bt) do { __builtin_amdgcn_s_setprio(1); _Pragma("unroll") for (int m = 0; m < 4; ++m) _Pragma("unroll") for (int n = 0; n < 2; ++n) _Pragma("unroll") for (int k = 0; k < 2; ++k) \
;         acc[ai][bj][m][n] = __builtin_amdgcn_mfma_f32_16x16x32_bf16(Bt[n][k], At[m][k], acc[ai][bj][m][n], 0, 0, 0); __builtin_amdgcn_s_setprio(0); } while (0)
; #define PG8_WAIT_V(n) asm volatile("s_waitcnt vmcnt(" #n ")" ::: "memory")
; #define PG8_WAIT_L(n) asm volatile("s_waitcnt lgkmcnt(" #n ")" ::: "memory")
; #define PG8_BAR __builtin_amdgcn_s_barrier()
; #define PG8_SCHED __builtin_amdgcn_sched_barrier(0)
; template <class Epi, class Sched, bool ALIGN_EPI = false, bool SP2 = false>
; __device__ __forceinline__ void gemm_phase(PG8_LAS unsigned char* lds, const Gemm g, const Sched& S, const Epi& E) {
;     ...
;             PG8_LDB(B0, 1, 0); PG8_LDB(B1, 1, 1); PG8_SCHED; PG8_LDA(At, 1, 0); PG8_STAGE(PG8_SA(0, 1), a2 + hstep, voffA);
;             PG8_WAIT_V(8); PG8_WAIT_L(0); PG8_BAR; PG8_MMA(0, 0, At, B0); PG8_MMA(0, 1, At, B1); PG8_BAR; PG8_SCHED;
	s_add_i32 s78, 0, 0x18000
	s_add_i32 s79, 0, 0x1c000
	v_add_u32_e32 v162, s78, v149
	v_add_u32_e32 v178, s79, v149
	ds_read_b128 v[144:147], v162
	ds_read_b128 v[154:157], v162 offset:1024
	ds_read_b128 v[158:161], v162 offset:2048
	ds_read_b128 v[162:165], v162 offset:3072
	ds_read_b128 v[166:169], v178
	ds_read_b128 v[170:173], v178 offset:1024
	ds_read_b128 v[174:177], v178 offset:2048
	ds_read_b128 v[178:181], v178 offset:3072
	s_add_u32 s54, s54, 0x80000
	s_addc_u32 s55, s55, 0
	s_mov_b32 m0, s60
	v_lshl_add_u64 v[224:225], s[54:55], 0, v[134:135]
	ds_read_b128 v[182:185], v153 offset:32768
	ds_read_b128 v[186:189], v153 offset:33792
	ds_read_b128 v[190:193], v153 offset:34816
	ds_read_b128 v[194:197], v153 offset:35840
	ds_read_b128 v[198:201], v153 offset:36864
	ds_read_b128 v[202:205], v153 offset:37888
	ds_read_b128 v[206:209], v153 offset:38912
	ds_read_b128 v[210:213], v153 offset:39936
	global_load_lds_dwordx4 v[224:225], off
	v_lshl_add_u64 v[224:225], s[54:55], 0, v[130:131]
	s_mov_b32 m0, s61
	s_nop 0
	global_load_lds_dwordx4 v[224:225], off
	s_waitcnt vmcnt(8)
	s_waitcnt lgkmcnt(0)
	s_barrier
	s_setprio 1
	s_waitcnt lgkmcnt(0)
	v_mfma_f32_16x16x32_bf16 v[124:127], v[144:147], v[182:185], v[124:127]
	v_mfma_f32_16x16x32_bf16 v[116:119], v[158:161], v[182:185], v[116:119]
	v_mfma_f32_16x16x32_bf16 v[108:111], v[144:147], v[190:193], v[108:111]
	v_mfma_f32_16x16x32_bf16 v[100:103], v[158:161], v[190:193], v[100:103]
	v_mfma_f32_16x16x32_bf16 v[92:95], v[144:147], v[198:201], v[92:95]
	v_mfma_f32_16x16x32_bf16 v[84:87], v[158:161], v[198:201], v[84:87]
	v_mfma_f32_16x16x32_bf16 v[76:79], v[144:147], v[206:209], v[76:79]
	v_mfma_f32_16x16x32_bf16 v[68:71], v[158:161], v[206:209], v[68:71]
	v_mfma_f32_16x16x32_bf16 v[124:127], v[154:157], v[186:189], v[124:127]
	v_mfma_f32_16x16x32_bf16 v[116:119], v[162:165], v[186:189], v[116:119]
	v_mfma_f32_16x16x32_bf16 v[108:111], v[154:157], v[194:197], v[108:111]
	v_mfma_f32_16x16x32_bf16 v[100:103], v[162:165], v[194:197], v[100:103]
	v_mfma_f32_16x16x32_bf16 v[92:95], v[154:157], v[202:205], v[92:95]
	v_mfma_f32_16x16x32_bf16 v[84:87], v[162:165], v[202:205], v[84:87]
	v_mfma_f32_16x16x32_bf16 v[76:79], v[154:157], v[210:213], v[76:79]
	v_mfma_f32_16x16x32_bf16 v[68:71], v[162:165], v[210:213], v[68:71]
	s_setprio 0
	s_setprio 1
	v_mfma_f32_16x16x32_bf16 v[120:123], v[166:169], v[182:185], v[120:123]
	v_mfma_f32_16x16x32_bf16 v[112:115], v[174:177], v[182:185], v[112:115]
	v_mfma_f32_16x16x32_bf16 v[104:107], v[166:169], v[190:193], v[104:107]
	v_mfma_f32_16x16x32_bf16 v[96:99], v[174:177], v[190:193], v[96:99]
	v_mfma_f32_16x16x32_bf16 v[88:91], v[166:169], v[198:201], v[88:91]
	v_mfma_f32_16x16x32_bf16 v[80:83], v[174:177], v[198:201], v[80:83]
	v_mfma_f32_16x16x32_bf16 v[72:75], v[166:169], v[206:209], v[72:75]
	v_mfma_f32_16x16x32_bf16 v[64:67], v[174:177], v[206:209], v[64:67]
	v_mfma_f32_16x16x32_bf16 v[120:123], v[170:173], v[186:189], v[120:123]
	v_mfma_f32_16x16x32_bf16 v[112:115], v[178:181], v[186:189], v[112:115]
	v_mfma_f32_16x16x32_bf16 v[104:107], v[170:173], v[194:197], v[104:107]
	v_mfma_f32_16x16x32_bf16 v[96:99], v[178:181], v[194:197], v[96:99]
	v_mfma_f32_16x16x32_bf16 v[88:91], v[170:173], v[202:205], v[88:91]
	v_mfma_f32_16x16x32_bf16 v[80:83], v[178:181], v[202:205], v[80:83]
	v_mfma_f32_16x16x32_bf16 v[72:75], v[170:173], v[210:213], v[72:75]
	v_mfma_f32_16x16x32_bf16 v[64:67], v[178:181], v[210:213], v[64:67]
	s_setprio 0
	s_barrier
; #define PG8_STAGE(bufoff, gbase, voff) do { _Pragma("unroll") for (int _i = 0; _i < 2; ++_i) \
;         __builtin_amdgcn_global_load_lds((const unsigned*)((const char*)(gbase) + (voff)[_i]), (PG8_LAS unsigned*)(lds + (bufoff) + ldsw + _i * 8192), 16, 0, 0); } while (0)
; #define PG8_LDA(dst, b, h) do { _Pragma("unroll") for (int m = 0; m < 4; ++m) _Pragma("unroll") for (int k = 0; k < 2; ++k) dst[m][k] = *(const PG8_LAS bf16x8*)(lds + PG8_SA(b, h) + aoff + m * 2048 + k * 1024); } while (0)
; #define PG8_MMA(ai, bj, At, Bt) do { __builtin_amdgcn_s_setprio(1); _Pragma("unroll") for (int m = 0; m < 4; ++m) _Pragma("unroll") for (int n = 0; n < 2; ++n) _Pragma("unroll") for (int k = 0; k < 2; ++k) \
;         acc[ai][bj][m][n] = __builtin_amdgcn_mfma_f32_16x16x32_bf16(Bt[n][k], At[m][k], acc[ai][bj][m][n], 0, 0, 0); __builtin_amdgcn_s_setprio(0); } while (0)
; #define PG8_WAIT_V(n) asm volatile("s_waitcnt vmcnt(" #n ")" ::: "memory")
; #define PG8_WAIT_L(n) asm volatile("s_waitcnt lgkmcnt(" #n ")" ::: "memory")
; #define PG8_BAR __builtin_amdgcn_s_barrier()
; #define PG8_SCHED __builtin_amdgcn_sched_barrier(0)
; template <class Epi, class Sched, bool ALIGN_EPI = false, bool SP2 = false>
; __device__ __forceinline__ void gemm_phase(PG8_LAS unsigned char* lds, const Gemm g, const Sched& S, const Epi& E) {
;     ...
;         for (int t = 0; t < nt; t += 2) {
;     ...
;             PG8_LDA(At, 1, 1); PG8_STAGE(PG8_SB(1, 0), b3, voffB); PG8_STAGE(PG8_SB(1, 1), b3 + hstep, voffB); PG8_STAGE(PG8_SA(1, 0), a3, voffA);
;             PG8_WAIT_V(8); PG8_WAIT_L(0); PG8_BAR; PG8_MMA(1, 0, At, B0); PG8_MMA(1, 1, At, B1); PG8_BAR; PG8_SCHED;
	s_add_i32 s54, s78, s56
	v_lshl_add_u64 v[214:215], v[214:215], 0, s[14:15]
	s_mov_b32 m0, s54
	ds_read_b128 v[182:185], v153 offset:49152
	ds_read_b128 v[186:189], v153 offset:50176
	ds_read_b128 v[190:193], v153 offset:51200
	ds_read_b128 v[194:197], v153 offset:52224
	ds_read_b128 v[198:201], v153 offset:53248
	ds_read_b128 v[202:205], v153 offset:54272
	ds_read_b128 v[206:209], v153 offset:55296
	ds_read_b128 v[210:213], v153 offset:56320
	global_load_lds_dwordx4 v[214:215], off
	s_add_i32 m0, s54, 0x2000
	s_add_u32 s50, s50, 0x80080
	v_lshl_add_u64 v[214:215], v[216:217], 0, s[14:15]
	s_addc_u32 s51, s51, 0
	s_add_i32 s54, s79, s56
	global_load_lds_dwordx4 v[214:215], off
	v_lshl_add_u64 v[214:215], s[50:51], 0, v[132:133]
	s_mov_b32 m0, s54
	s_nop 0
	global_load_lds_dwordx4 v[214:215], off
	v_lshl_add_u64 v[214:215], s[50:51], 0, v[128:129]
	s_add_i32 m0, s54, 0x2000
	s_nop 0
	global_load_lds_dwordx4 v[214:215], off
	v_lshl_add_u64 v[214:215], v[220:221], 0, s[14:15]
	s_mov_b32 m0, s63
	s_nop 0
	global_load_lds_dwordx4 v[214:215], off
	v_lshl_add_u64 v[214:215], v[222:223], 0, s[14:15]
	s_mov_b32 m0, s64
	s_nop 0
	global_load_lds_dwordx4 v[214:215], off
	s_waitcnt vmcnt(8)
	s_waitcnt lgkmcnt(0)
	s_barrier
	s_setprio 1
	s_waitcnt lgkmcnt(0)
	v_mfma_f32_16x16x32_bf16 v[60:63], v[144:147], v[182:185], v[60:63]
	v_mfma_f32_16x16x32_bf16 v[52:55], v[158:161], v[182:185], v[52:55]
	v_mfma_f32_16x16x32_bf16 v[44:47], v[144:147], v[190:193], v[44:47]
	v_mfma_f32_16x16x32_bf16 v[36:39], v[158:161], v[190:193], v[36:39]
	v_mfma_f32_16x16x32_bf16 v[28:31], v[144:147], v[198:201], v[28:31]
	v_mfma_f32_16x16x32_bf16 v[20:23], v[158:161], v[198:201], v[20:23]
	v_mfma_f32_16x16x32_bf16 v[12:15], v[144:147], v[206:209], v[12:15]
	v_mfma_f32_16x16x32_bf16 v[4:7], v[158:161], v[206:209], v[4:7]
	v_mfma_f32_16x16x32_bf16 v[60:63], v[154:157], v[186:189], v[60:63]
	v_mfma_f32_16x16x32_bf16 v[52:55], v[162:165], v[186:189], v[52:55]
	v_mfma_f32_16x16x32_bf16 v[44:47], v[154:157], v[194:197], v[44:47]
	v_mfma_f32_16x16x32_bf16 v[36:39], v[162:165], v[194:197], v[36:39]
	v_mfma_f32_16x16x32_bf16 v[28:31], v[154:157], v[202:205], v[28:31]
	v_mfma_f32_16x16x32_bf16 v[20:23], v[162:165], v[202:205], v[20:23]
	v_mfma_f32_16x16x32_bf16 v[12:15], v[154:157], v[210:213], v[12:15]
	v_mfma_f32_16x16x32_bf16 v[4:7], v[162:165], v[210:213], v[4:7]
	s_setprio 0
	s_setprio 1
	v_mfma_f32_16x16x32_bf16 v[56:59], v[166:169], v[182:185], v[56:59]
	v_mfma_f32_16x16x32_bf16 v[48:51], v[174:177], v[182:185], v[48:51]
	v_mfma_f32_16x16x32_bf16 v[40:43], v[166:169], v[190:193], v[40:43]
	v_mfma_f32_16x16x32_bf16 v[32:35], v[174:177], v[190:193], v[32:35]
	v_mfma_f32_16x16x32_bf16 v[24:27], v[166:169], v[198:201], v[24:27]
	v_mfma_f32_16x16x32_bf16 v[16:19], v[174:177], v[198:201], v[16:19]
	v_mfma_f32_16x16x32_bf16 v[8:11], v[166:169], v[206:209], v[8:11]
	v_mfma_f32_16x16x32_bf16 v[0:3], v[174:177], v[206:209], v[0:3]
	v_mfma_f32_16x16x32_bf16 v[56:59], v[170:173], v[186:189], v[56:59]
	v_mfma_f32_16x16x32_bf16 v[48:51], v[178:181], v[186:189], v[48:51]
	v_mfma_f32_16x16x32_bf16 v[40:43], v[170:173], v[194:197], v[40:43]
	v_mfma_f32_16x16x32_bf16 v[32:35], v[178:181], v[194:197], v[32:35]
	v_mfma_f32_16x16x32_bf16 v[24:27], v[170:173], v[202:205], v[24:27]
	v_mfma_f32_16x16x32_bf16 v[16:19], v[178:181], v[202:205], v[16:19]
	v_mfma_f32_16x16x32_bf16 v[8:11], v[170:173], v[210:213], v[8:11]
	v_mfma_f32_16x16x32_bf16 v[0:3], v[178:181], v[210:213], v[0:3]
	s_setprio 0
	s_barrier
	s_add_i32 s77, s77, 2
	s_add_u32 s48, s48, 0x100
	s_addc_u32 s49, s49, 0
	s_add_u32 s75, s75, 0x100
	s_addc_u32 s76, s76, 0

; #define PG8_STAGE(bufoff, gbase, voff) do { _Pragma("unroll") for (int _i = 0; _i < 2; ++_i) \
;         __builtin_amdgcn_global_load_lds((const unsigned*)((const char*)(gbase) + (voff)[_i]), (PG8_LAS unsigned*)(lds + (bufoff) + ldsw + _i * 8192), 16, 0, 0); } while (0)
; #define PG8_LDA(dst, b, h) do { _Pragma("unroll") for (int m = 0; m < 4; ++m) _Pragma("unroll") for (int k = 0; k < 2; ++k) dst[m][k] = *(const PG8_LAS bf16x8*)(lds + PG8_SA(b, h) + aoff + m * 2048 + k * 1024); } while (0)
; #define PG8_LDB(dst, b, h) do { _Pragma("unroll") for (int n = 0; n < 2; ++n) _Pragma("unroll") for (int k = 0; k < 2; ++k) dst[n][k] = *(const PG8_LAS bf16x8*)(lds + PG8_SB(b, h) + boff + n * 2048 + k * 1024); } while (0)
; #define PG8_MMA(ai, bj, At, Bt) do { __builtin_amdgcn_s_setprio(1); _Pragma("unroll") for (int m = 0; m < 4; ++m) _Pragma("unroll") for (int n = 0; n < 2; ++n) _Pragma("unroll") for (int k = 0; k < 2; ++k) \
;         acc[ai][bj][m][n] = __builtin_amdgcn_mfma_f32_16x16x32_bf16(Bt[n][k], At[m][k], acc[ai][bj][m][n], 0, 0, 0); __builtin_amdgcn_s_setprio(0); } while (0)
; #define PG8_WAIT_V(n) asm volatile("s_waitcnt vmcnt(" #n ")" ::: "memory")
; #define PG8_WAIT_L(n) asm volatile("s_waitcnt lgkmcnt(" #n ")" ::: "memory")
; #define PG8_BAR __builtin_amdgcn_s_barrier()
; #define PG8_SCHED __builtin_amdgcn_sched_barrier(0)
; template <class Epi, class Sched, bool ALIGN_EPI = false, bool SP2 = false>
; __device__ __forceinline__ void gemm_phase(PG8_LAS unsigned char* lds, const Gemm g, const Sched& S, const Epi& E) {
;     ...
;             PG8_LDB(B0, 0, 0); PG8_LDB(B1, 0, 1); PG8_SCHED; PG8_LDA(At, 0, 0); PG8_STAGE(PG8_SA(1, 1), a1 + hstep, voffA);
;             PG8_WAIT_V(8); PG8_WAIT_L(0); PG8_BAR; PG8_MMA(0, 0, At, B0); PG8_MMA(0, 1, At, B1); PG8_BAR; PG8_SCHED;
;     ...
;         for (int a = 0; a < 2; ++a)
; #pragma unroll
;             for (int b = 0; b < 2; ++b)
; #pragma unroll
;                 for (int m = 0; m < 4; ++m)
; #pragma unroll
;                     for (int n = 0; n < 2; ++n) acc[a][b][m][n] = (f32x4){0.f, 0.f, 0.f, 0.f};
;         cur = nxt; cA = nA; cB = nB; ++ui;
.LBB0_345:
	s_ashr_i32 s45, s44, 31
	s_lshl_b64 s[46:47], s[44:45], 20
	s_add_u32 s46, s31, s46
	s_addc_u32 s47, s35, s47
	s_and_b64 s[48:49], s[2:3], exec
	s_cselect_b32 s45, s47, s51
	s_cselect_b32 s74, s46, s50
	s_ashr_i32 s43, s42, 31
	s_lshl_b64 s[48:49], s[42:43], 20
	s_add_u32 s48, s56, s48
	s_addc_u32 s49, s57, s49
	s_and_b64 s[54:55], s[2:3], exec
	s_cselect_b32 s43, s49, s53
	s_cselect_b32 s75, s48, s52
	s_add_u32 s50, s50, 0x80080
	s_addc_u32 s51, s51, 0
	s_add_u32 s76, s52, 0x100
	v_mov_b32_e32 v0, 0
	s_addc_u32 s77, s53, 0
	s_mov_b32 s78, -2
	v_mov_b32_e32 v1, v0
	v_mov_b32_e32 v2, v0
	v_mov_b32_e32 v3, v0
	v_mov_b32_e32 v4, v0
	v_mov_b32_e32 v5, v0
	v_mov_b32_e32 v6, v0
	v_mov_b32_e32 v7, v0
	v_mov_b32_e32 v16, v0
	v_mov_b32_e32 v17, v0
	v_mov_b32_e32 v18, v0
	v_mov_b32_e32 v19, v0
	v_mov_b32_e32 v20, v0
	v_mov_b32_e32 v21, v0
	v_mov_b32_e32 v22, v0
	v_mov_b32_e32 v23, v0
	v_mov_b32_e32 v32, v0
	v_mov_b32_e32 v33, v0
	v_mov_b32_e32 v34, v0
	v_mov_b32_e32 v35, v0
	v_mov_b32_e32 v36, v0
	v_mov_b32_e32 v37, v0
	v_mov_b32_e32 v38, v0
	v_mov_b32_e32 v39, v0
	v_mov_b32_e32 v48, v0
	v_mov_b32_e32 v49, v0
	v_mov_b32_e32 v50, v0
	v_mov_b32_e32 v51, v0
	v_mov_b32_e32 v52, v0
	v_mov_b32_e32 v53, v0
	v_mov_b32_e32 v54, v0
	v_mov_b32_e32 v55, v0
	v_mov_b32_e32 v8, v0
	v_mov_b32_e32 v9, v0
	v_mov_b32_e32 v10, v0
	v_mov_b32_e32 v11, v0
	v_mov_b32_e32 v12, v0
	v_mov_b32_e32 v13, v0
	v_mov_b32_e32 v14, v0
	v_mov_b32_e32 v15, v0
	v_mov_b32_e32 v24, v0
	v_mov_b32_e32 v25, v0
	v_mov_b32_e32 v26, v0
	v_mov_b32_e32 v27, v0
	v_mov_b32_e32 v28, v0
	v_mov_b32_e32 v29, v0
	v_mov_b32_e32 v30, v0
	v_mov_b32_e32 v31, v0
	v_mov_b32_e32 v40, v0
	v_mov_b32_e32 v41, v0
	v_mov_b32_e32 v42, v0
	v_mov_b32_e32 v43, v0
	v_mov_b32_e32 v44, v0
	v_mov_b32_e32 v45, v0
	v_mov_b32_e32 v46, v0
	v_mov_b32_e32 v47, v0
	v_mov_b32_e32 v56, v0
	v_mov_b32_e32 v57, v0
	v_mov_b32_e32 v58, v0
	v_mov_b32_e32 v59, v0
	v_mov_b32_e32 v60, v0
	v_mov_b32_e32 v61, v0
	v_mov_b32_e32 v62, v0
	v_mov_b32_e32 v63, v0
	v_mov_b32_e32 v64, v0
	v_mov_b32_e32 v65, v0
	v_mov_b32_e32 v66, v0
	v_mov_b32_e32 v67, v0
	v_mov_b32_e32 v68, v0
	v_mov_b32_e32 v69, v0
	v_mov_b32_e32 v70, v0
	v_mov_b32_e32 v71, v0
	v_mov_b32_e32 v80, v0
	v_mov_b32_e32 v81, v0
	v_mov_b32_e32 v82, v0
	v_mov_b32_e32 v83, v0
	v_mov_b32_e32 v84, v0
	v_mov_b32_e32 v85, v0
	v_mov_b32_e32 v86, v0
	v_mov_b32_e32 v87, v0
	v_mov_b32_e32 v96, v0
	v_mov_b32_e32 v97, v0
	v_mov_b32_e32 v98, v0
	v_mov_b32_e32 v99, v0
	v_mov_b32_e32 v100, v0
	v_mov_b32_e32 v101, v0
	v_mov_b32_e32 v102, v0
	v_mov_b32_e32 v103, v0
	v_mov_b32_e32 v112, v0
	v_mov_b32_e32 v113, v0
	v_mov_b32_e32 v114, v0
	v_mov_b32_e32 v115, v0
	v_mov_b32_e32 v116, v0
	v_mov_b32_e32 v117, v0
	v_mov_b32_e32 v118, v0
	v_mov_b32_e32 v119, v0
	v_mov_b32_e32 v72, v0
	v_mov_b32_e32 v73, v0
	v_mov_b32_e32 v74, v0
	v_mov_b32_e32 v75, v0
	v_mov_b32_e32 v76, v0
	v_mov_b32_e32 v77, v0
	v_mov_b32_e32 v78, v0
	v_mov_b32_e32 v79, v0
	v_mov_b32_e32 v88, v0
	v_mov_b32_e32 v89, v0
	v_mov_b32_e32 v90, v0
	v_mov_b32_e32 v91, v0
	v_mov_b32_e32 v92, v0
	v_mov_b32_e32 v93, v0
	v_mov_b32_e32 v94, v0
	v_mov_b32_e32 v95, v0
	v_mov_b32_e32 v104, v0
	v_mov_b32_e32 v105, v0
	v_mov_b32_e32 v106, v0
	v_mov_b32_e32 v107, v0
	v_mov_b32_e32 v108, v0
	v_mov_b32_e32 v109, v0
	v_mov_b32_e32 v110, v0
	v_mov_b32_e32 v111, v0
	v_mov_b32_e32 v120, v0
	v_mov_b32_e32 v121, v0
	v_mov_b32_e32 v122, v0
	v_mov_b32_e32 v123, v0
	v_mov_b32_e32 v124, v0
	v_mov_b32_e32 v125, v0
	v_mov_b32_e32 v126, v0
	v_mov_b32_e32 v127, v0
	s_cmp_eq_u32 s63, 1
	s_cbranch_scc1 .LBB0_346
	ds_read_b128 v[144:147], v155
	ds_read_b128 v[148:151], v155 offset:1024
	ds_read_b128 v[160:163], v155 offset:2048
	ds_read_b128 v[164:167], v155 offset:3072
	ds_read_b128 v[168:171], v156
	ds_read_b128 v[172:175], v156 offset:1024
	ds_read_b128 v[176:179], v156 offset:2048
	ds_read_b128 v[180:183], v156 offset:3072
	s_add_u32 s52, s50, 0xfff80080
	s_addc_u32 s53, s51, -1
	s_cmp_eq_u32 s78, 28
	s_cselect_b32 s55, s45, s53
	s_cselect_b32 s54, s74, s52
	s_cselect_b32 s53, s43, s77
	s_cselect_b32 s52, s75, s76
	v_lshl_add_u64 v[216:217], s[50:51], 0, v[136:137]
	s_add_i32 m0, s28, 0xc000
	ds_read_b128 v[184:187], v157
	ds_read_b128 v[188:191], v157 offset:1024
	ds_read_b128 v[192:195], v157 offset:2048
	ds_read_b128 v[196:199], v157 offset:3072
	ds_read_b128 v[200:203], v157 offset:4096
	ds_read_b128 v[204:207], v157 offset:5120
	ds_read_b128 v[208:211], v157 offset:6144
	ds_read_b128 v[212:215], v157 offset:7168
	global_load_lds_dwordx4 v[216:217], off
	v_lshl_add_u64 v[216:217], s[50:51], 0, v[138:139]
	s_add_i32 m0, s28, 0xe000
	s_nop 0
	global_load_lds_dwordx4 v[216:217], off
	s_waitcnt vmcnt(24)
	s_waitcnt lgkmcnt(0)
	s_barrier
; #define PG8_STAGE(bufoff, gbase, voff) do { _Pragma("unroll") for (int _i = 0; _i < 2; ++_i) \
;         __builtin_amdgcn_global_load_lds((const unsigned*)((const char*)(gbase) + (voff)[_i]), (PG8_LAS unsigned*)(lds + (bufoff) + ldsw + _i * 8192), 16, 0, 0); } while (0)
; #define PG8_LDA(dst, b, h) do { _Pragma("unroll") for (int m = 0; m < 4; ++m) _Pragma("unroll") for (int k = 0; k < 2; ++k) dst[m][k] = *(const PG8_LAS bf16x8*)(lds + PG8_SA(b, h) + aoff + m * 2048 + k * 1024); } while (0)
; #define PG8_MMA(ai, bj, At, Bt) do { __builtin_amdgcn_s_setprio(1); _Pragma("unroll") for (int m = 0; m < 4; ++m) _Pragma("unroll") for (int n = 0; n < 2; ++n) _Pragma("unroll") for (int k = 0; k < 2; ++k) \
;         acc[ai][bj][m][n] = __builtin_amdgcn_mfma_f32_16x16x32_bf16(Bt[n][k], At[m][k], acc[ai][bj][m][n], 0, 0, 0); __builtin_amdgcn_s_setprio(0); } while (0)
; #define PG8_WAIT_V(n) asm volatile("s_waitcnt vmcnt(" #n ")" ::: "memory")
; #define PG8_WAIT_L(n) asm volatile("s_waitcnt lgkmcnt(" #n ")" ::: "memory")
; #define PG8_BAR __builtin_amdgcn_s_barrier()
; #define PG8_SCHED __builtin_amdgcn_sched_barrier(0)
; template <class Epi, class Sched, bool ALIGN_EPI = false, bool SP2 = false>
; __device__ __forceinline__ void gemm_phase(PG8_LAS unsigned char* lds, const Gemm g, const Sched& S, const Epi& E) {
;     ...
;             PG8_WAIT_V(8); PG8_WAIT_L(0); PG8_BAR; PG8_MMA(0, 0, At, B0); PG8_MMA(0, 1, At, B1); PG8_BAR; PG8_SCHED;
;             PG8_LDA(At, 0, 1); PG8_STAGE(PG8_SB(0, 0), b2, voffB); PG8_STAGE(PG8_SB(0, 1), b2 + hstep, voffB); PG8_STAGE(PG8_SA(0, 0), a2, voffA);
;             PG8_WAIT_V(8); PG8_WAIT_L(0); PG8_BAR; PG8_MMA(1, 0, At, B0); PG8_MMA(1, 1, At, B1); PG8_BAR; PG8_SCHED;
	s_setprio 1
	s_waitcnt lgkmcnt(0)
	v_mfma_f32_16x16x32_bf16 v[124:127], v[144:147], v[184:187], v[124:127]
	v_mfma_f32_16x16x32_bf16 v[120:123], v[160:163], v[184:187], v[120:123]
	v_mfma_f32_16x16x32_bf16 v[108:111], v[144:147], v[192:195], v[108:111]
	v_mfma_f32_16x16x32_bf16 v[104:107], v[160:163], v[192:195], v[104:107]
	v_mfma_f32_16x16x32_bf16 v[92:95], v[144:147], v[200:203], v[92:95]
	v_mfma_f32_16x16x32_bf16 v[88:91], v[160:163], v[200:203], v[88:91]
	v_mfma_f32_16x16x32_bf16 v[76:79], v[144:147], v[208:211], v[76:79]
	v_mfma_f32_16x16x32_bf16 v[72:75], v[160:163], v[208:211], v[72:75]
	v_mfma_f32_16x16x32_bf16 v[124:127], v[148:151], v[188:191], v[124:127]
	v_mfma_f32_16x16x32_bf16 v[120:123], v[164:167], v[188:191], v[120:123]
	v_mfma_f32_16x16x32_bf16 v[108:111], v[148:151], v[196:199], v[108:111]
	v_mfma_f32_16x16x32_bf16 v[104:107], v[164:167], v[196:199], v[104:107]
	v_mfma_f32_16x16x32_bf16 v[92:95], v[148:151], v[204:207], v[92:95]
	v_mfma_f32_16x16x32_bf16 v[88:91], v[164:167], v[204:207], v[88:91]
	v_mfma_f32_16x16x32_bf16 v[76:79], v[148:151], v[212:215], v[76:79]
	v_mfma_f32_16x16x32_bf16 v[72:75], v[164:167], v[212:215], v[72:75]
	s_setprio 0
	s_setprio 1
	v_mfma_f32_16x16x32_bf16 v[116:119], v[168:171], v[184:187], v[116:119]
	v_mfma_f32_16x16x32_bf16 v[112:115], v[176:179], v[184:187], v[112:115]
	v_mfma_f32_16x16x32_bf16 v[100:103], v[168:171], v[192:195], v[100:103]
	v_mfma_f32_16x16x32_bf16 v[96:99], v[176:179], v[192:195], v[96:99]
	v_mfma_f32_16x16x32_bf16 v[84:87], v[168:171], v[200:203], v[84:87]
	v_mfma_f32_16x16x32_bf16 v[80:83], v[176:179], v[200:203], v[80:83]
	v_mfma_f32_16x16x32_bf16 v[68:71], v[168:171], v[208:211], v[68:71]
	v_mfma_f32_16x16x32_bf16 v[64:67], v[176:179], v[208:211], v[64:67]
	v_mfma_f32_16x16x32_bf16 v[116:119], v[172:175], v[188:191], v[116:119]
	v_mfma_f32_16x16x32_bf16 v[112:115], v[180:183], v[188:191], v[112:115]
	v_mfma_f32_16x16x32_bf16 v[100:103], v[172:175], v[196:199], v[100:103]
	v_mfma_f32_16x16x32_bf16 v[96:99], v[180:183], v[196:199], v[96:99]
	v_mfma_f32_16x16x32_bf16 v[84:87], v[172:175], v[204:207], v[84:87]
	v_mfma_f32_16x16x32_bf16 v[80:83], v[180:183], v[204:207], v[80:83]
	v_mfma_f32_16x16x32_bf16 v[68:71], v[172:175], v[212:215], v[68:71]
	v_mfma_f32_16x16x32_bf16 v[64:67], v[180:183], v[212:215], v[64:67]
	s_setprio 0
	s_barrier
	s_add_i32 s79, s67, s58
	v_lshl_add_u64 v[216:217], s[52:53], 0, v[132:133]
	s_mov_b32 m0, s79
	ds_read_b128 v[184:187], v157 offset:16384
	ds_read_b128 v[188:191], v157 offset:17408
	ds_read_b128 v[192:195], v157 offset:18432
	ds_read_b128 v[196:199], v157 offset:19456
	ds_read_b128 v[200:203], v157 offset:20480
	ds_read_b128 v[204:207], v157 offset:21504
	ds_read_b128 v[208:211], v157 offset:22528
	ds_read_b128 v[212:215], v157 offset:23552
	global_load_lds_dwordx4 v[216:217], off
	s_add_i32 m0, s79, 0x2000
	s_add_u32 s80, s52, 0x80000
	v_lshl_add_u64 v[220:221], s[52:53], 0, v[128:129]
	s_addc_u32 s81, s53, 0
	s_add_i32 s79, s71, s58
	global_load_lds_dwordx4 v[220:221], off
	v_lshl_add_u64 v[222:223], s[80:81], 0, v[132:133]
	s_mov_b32 m0, s79
	v_lshl_add_u64 v[224:225], s[54:55], 0, v[130:131]
	global_load_lds_dwordx4 v[222:223], off
	v_lshl_add_u64 v[222:223], s[80:81], 0, v[128:129]
	s_add_i32 m0, s79, 0x2000
	s_nop 0
	global_load_lds_dwordx4 v[222:223], off
	v_lshl_add_u64 v[222:223], s[54:55], 0, v[134:135]
	s_mov_b32 m0, s28
	s_nop 0
	global_load_lds_dwordx4 v[222:223], off
	s_mov_b32 m0, s29
	s_nop 0
	global_load_lds_dwordx4 v[224:225], off
	s_waitcnt vmcnt(24)
	s_waitcnt lgkmcnt(0)
	s_barrier
	s_setprio 1
	s_waitcnt lgkmcnt(0)
	v_mfma_f32_16x16x32_bf16 v[60:63], v[144:147], v[184:187], v[60:63]
	v_mfma_f32_16x16x32_bf16 v[56:59], v[160:163], v[184:187], v[56:59]
	v_mfma_f32_16x16x32_bf16 v[44:47], v[144:147], v[192:195], v[44:47]
	v_mfma_f32_16x16x32_bf16 v[40:43], v[160:163], v[192:195], v[40:43]
	v_mfma_f32_16x16x32_bf16 v[28:31], v[144:147], v[200:203], v[28:31]
	v_mfma_f32_16x16x32_bf16 v[24:27], v[160:163], v[200:203], v[24:27]
	v_mfma_f32_16x16x32_bf16 v[12:15], v[144:147], v[208:211], v[12:15]
	v_mfma_f32_16x16x32_bf16 v[8:11], v[160:163], v[208:211], v[8:11]
	v_mfma_f32_16x16x32_bf16 v[60:63], v[148:151], v[188:191], v[60:63]
	v_mfma_f32_16x16x32_bf16 v[56:59], v[164:167], v[188:191], v[56:59]
	v_mfma_f32_16x16x32_bf16 v[44:47], v[148:151], v[196:199], v[44:47]
	v_mfma_f32_16x16x32_bf16 v[40:43], v[164:167], v[196:199], v[40:43]
	v_mfma_f32_16x16x32_bf16 v[28:31], v[148:151], v[204:207], v[28:31]
	v_mfma_f32_16x16x32_bf16 v[24:27], v[164:167], v[204:207], v[24:27]
	v_mfma_f32_16x16x32_bf16 v[12:15], v[148:151], v[212:215], v[12:15]
	v_mfma_f32_16x16x32_bf16 v[8:11], v[164:167], v[212:215], v[8:11]
	s_setprio 0
	s_setprio 1
	v_mfma_f32_16x16x32_bf16 v[52:55], v[168:171], v[184:187], v[52:55]
	v_mfma_f32_16x16x32_bf16 v[48:51], v[176:179], v[184:187], v[48:51]
	v_mfma_f32_16x16x32_bf16 v[36:39], v[168:171], v[192:195], v[36:39]
	v_mfma_f32_16x16x32_bf16 v[32:35], v[176:179], v[192:195], v[32:35]
	v_mfma_f32_16x16x32_bf16 v[20:23], v[168:171], v[200:203], v[20:23]
	v_mfma_f32_16x16x32_bf16 v[16:19], v[176:179], v[200:203], v[16:19]
	v_mfma_f32_16x16x32_bf16 v[4:7], v[168:171], v[208:211], v[4:7]
	v_mfma_f32_16x16x32_bf16 v[0:3], v[176:179], v[208:211], v[0:3]
	v_mfma_f32_16x16x32_bf16 v[52:55], v[172:175], v[188:191], v[52:55]
	v_mfma_f32_16x16x32_bf16 v[48:51], v[180:183], v[188:191], v[48:51]
	v_mfma_f32_16x16x32_bf16 v[36:39], v[172:175], v[196:199], v[36:39]
	v_mfma_f32_16x16x32_bf16 v[32:35], v[180:183], v[196:199], v[32:35]
	v_mfma_f32_16x16x32_bf16 v[20:23], v[172:175], v[204:207], v[20:23]
	v_mfma_f32_16x16x32_bf16 v[16:19], v[180:183], v[204:207], v[16:19]
	v_mfma_f32_16x16x32_bf16 v[4:7], v[172:175], v[212:215], v[4:7]
	v_mfma_f32_16x16x32_bf16 v[0:3], v[180:183], v[212:215], v[0:3]
	s_setprio 0
	s_barrier
; #define PG8_STAGE(bufoff, gbase, voff) do { _Pragma("unroll") for (int _i = 0; _i < 2; ++_i) \
;         __builtin_amdgcn_global_load_lds((const unsigned*)((const char*)(gbase) + (voff)[_i]), (PG8_LAS unsigned*)(lds + (bufoff) + ldsw + _i * 8192), 16, 0, 0); } while (0)
; #define PG8_LDA(dst, b, h) do { _Pragma("unroll") for (int m = 0; m < 4; ++m) _Pragma("unroll") for (int k = 0; k < 2; ++k) dst[m][k] = *(const PG8_LAS bf16x8*)(lds + PG8_SA(b, h) + aoff + m * 2048 + k * 1024); } while (0)
; #define PG8_LDB(dst, b, h) do { _Pragma("unroll") for (int n = 0; n < 2; ++n) _Pragma("unroll") for (int k = 0; k < 2; ++k) dst[n][k] = *(const PG8_LAS bf16x8*)(lds + PG8_SB(b, h) + boff + n * 2048 + k * 1024); } while (0)
; #define PG8_MMA(ai, bj, At, Bt) do { __builtin_amdgcn_s_setprio(1); _Pragma("unroll") for (int m = 0; m < 4; ++m) _Pragma("unroll") for (int n = 0; n < 2; ++n) _Pragma("unroll") for (int k = 0; k < 2; ++k) \
;         acc[ai][bj][m][n] = __builtin_amdgcn_mfma_f32_16x16x32_bf16(Bt[n][k], At[m][k], acc[ai][bj][m][n], 0, 0, 0); __builtin_amdgcn_s_setprio(0); } while (0)
; #define PG8_WAIT_V(n) asm volatile("s_waitcnt vmcnt(" #n ")" ::: "memory")
; #define PG8_WAIT_L(n) asm volatile("s_waitcnt lgkmcnt(" #n ")" ::: "memory")
; #define PG8_BAR __builtin_amdgcn_s_barrier()
; #define PG8_SCHED __builtin_amdgcn_sched_barrier(0)
; template <class Epi, class Sched, bool ALIGN_EPI = false, bool SP2 = false>
; __device__ __forceinline__ void gemm_phase(PG8_LAS unsigned char* lds, const Gemm g, const Sched& S, const Epi& E) {
;     ...
;             PG8_LDB(B0, 1, 0); PG8_LDB(B1, 1, 1); PG8_SCHED; PG8_LDA(At, 1, 0); PG8_STAGE(PG8_SA(0, 1), a2 + hstep, voffA);
;             PG8_WAIT_V(8); PG8_WAIT_L(0); PG8_BAR; PG8_MMA(0, 0, At, B0); PG8_MMA(0, 1, At, B1); PG8_BAR; PG8_SCHED;
	s_add_i32 s79, 0, 0x18000
	s_add_i32 s80, 0, 0x1c000
	v_add_u32_e32 v164, s79, v153
	v_add_u32_e32 v180, s80, v153
	ds_read_b128 v[144:147], v164
	ds_read_b128 v[148:151], v164 offset:1024
	ds_read_b128 v[160:163], v164 offset:2048
	ds_read_b128 v[164:167], v164 offset:3072
	ds_read_b128 v[168:171], v180
	ds_read_b128 v[172:175], v180 offset:1024
	ds_read_b128 v[176:179], v180 offset:2048
	ds_read_b128 v[180:183], v180 offset:3072
	s_add_u32 s54, s54, 0x80000
	s_addc_u32 s55, s55, 0
	s_mov_b32 m0, s61
	v_lshl_add_u64 v[226:227], s[54:55], 0, v[134:135]
	ds_read_b128 v[184:187], v157 offset:32768
	ds_read_b128 v[188:191], v157 offset:33792
	ds_read_b128 v[192:195], v157 offset:34816
	ds_read_b128 v[196:199], v157 offset:35840
	ds_read_b128 v[200:203], v157 offset:36864
	ds_read_b128 v[204:207], v157 offset:37888
	ds_read_b128 v[208:211], v157 offset:38912
	ds_read_b128 v[212:215], v157 offset:39936
	global_load_lds_dwordx4 v[226:227], off
	v_lshl_add_u64 v[226:227], s[54:55], 0, v[130:131]
	s_mov_b32 m0, s62
	s_nop 0
	global_load_lds_dwordx4 v[226:227], off
	s_waitcnt vmcnt(8)
	s_waitcnt lgkmcnt(0)
	s_barrier
	s_setprio 1
	s_waitcnt lgkmcnt(0)
	v_mfma_f32_16x16x32_bf16 v[124:127], v[144:147], v[184:187], v[124:127]
	v_mfma_f32_16x16x32_bf16 v[120:123], v[160:163], v[184:187], v[120:123]
	v_mfma_f32_16x16x32_bf16 v[108:111], v[144:147], v[192:195], v[108:111]
	v_mfma_f32_16x16x32_bf16 v[104:107], v[160:163], v[192:195], v[104:107]
	v_mfma_f32_16x16x32_bf16 v[92:95], v[144:147], v[200:203], v[92:95]
	v_mfma_f32_16x16x32_bf16 v[88:91], v[160:163], v[200:203], v[88:91]
	v_mfma_f32_16x16x32_bf16 v[76:79], v[144:147], v[208:211], v[76:79]
	v_mfma_f32_16x16x32_bf16 v[72:75], v[160:163], v[208:211], v[72:75]
	v_mfma_f32_16x16x32_bf16 v[124:127], v[148:151], v[188:191], v[124:127]
	v_mfma_f32_16x16x32_bf16 v[120:123], v[164:167], v[188:191], v[120:123]
	v_mfma_f32_16x16x32_bf16 v[108:111], v[148:151], v[196:199], v[108:111]
	v_mfma_f32_16x16x32_bf16 v[104:107], v[164:167], v[196:199], v[104:107]
	v_mfma_f32_16x16x32_bf16 v[92:95], v[148:151], v[204:207], v[92:95]
	v_mfma_f32_16x16x32_bf16 v[88:91], v[164:167], v[204:207], v[88:91]
	v_mfma_f32_16x16x32_bf16 v[76:79], v[148:151], v[212:215], v[76:79]
	v_mfma_f32_16x16x32_bf16 v[72:75], v[164:167], v[212:215], v[72:75]
	s_setprio 0
	s_setprio 1
	v_mfma_f32_16x16x32_bf16 v[116:119], v[168:171], v[184:187], v[116:119]
	v_mfma_f32_16x16x32_bf16 v[112:115], v[176:179], v[184:187], v[112:115]
	v_mfma_f32_16x16x32_bf16 v[100:103], v[168:171], v[192:195], v[100:103]
	v_mfma_f32_16x16x32_bf16 v[96:99], v[176:179], v[192:195], v[96:99]
	v_mfma_f32_16x16x32_bf16 v[84:87], v[168:171], v[200:203], v[84:87]
	v_mfma_f32_16x16x32_bf16 v[80:83], v[176:179], v[200:203], v[80:83]
	v_mfma_f32_16x16x32_bf16 v[68:71], v[168:171], v[208:211], v[68:71]
	v_mfma_f32_16x16x32_bf16 v[64:67], v[176:179], v[208:211], v[64:67]
	v_mfma_f32_16x16x32_bf16 v[116:119], v[172:175], v[188:191], v[116:119]
	v_mfma_f32_16x16x32_bf16 v[112:115], v[180:183], v[188:191], v[112:115]
	v_mfma_f32_16x16x32_bf16 v[100:103], v[172:175], v[196:199], v[100:103]
	v_mfma_f32_16x16x32_bf16 v[96:99], v[180:183], v[196:199], v[96:99]
	v_mfma_f32_16x16x32_bf16 v[84:87], v[172:175], v[204:207], v[84:87]
	v_mfma_f32_16x16x32_bf16 v[80:83], v[180:183], v[204:207], v[80:83]
	v_mfma_f32_16x16x32_bf16 v[68:71], v[172:175], v[212:215], v[68:71]
	v_mfma_f32_16x16x32_bf16 v[64:67], v[180:183], v[212:215], v[64:67]
	s_setprio 0
	s_barrier
; #define PG8_STAGE(bufoff, gbase, voff) do { _Pragma("unroll") for (int _i = 0; _i < 2; ++_i) \
;         __builtin_amdgcn_global_load_lds((const unsigned*)((const char*)(gbase) + (voff)[_i]), (PG8_LAS unsigned*)(lds + (bufoff) + ldsw + _i * 8192), 16, 0, 0); } while (0)
; #define PG8_LDA(dst, b, h) do { _Pragma("unroll") for (int m = 0; m < 4; ++m) _Pragma("unroll") for (int k = 0; k < 2; ++k) dst[m][k] = *(const PG8_LAS bf16x8*)(lds + PG8_SA(b, h) + aoff + m * 2048 + k * 1024); } while (0)
; #define PG8_MMA(ai, bj, At, Bt) do { __builtin_amdgcn_s_setprio(1); _Pragma("unroll") for (int m = 0; m < 4; ++m) _Pragma("unroll") for (int n = 0; n < 2; ++n) _Pragma("unroll") for (int k = 0; k < 2; ++k) \
;         acc[ai][bj][m][n] = __builtin_amdgcn_mfma_f32_16x16x32_bf16(Bt[n][k], At[m][k], acc[ai][bj][m][n], 0, 0, 0); __builtin_amdgcn_s_setprio(0); } while (0)
; #define PG8_WAIT_V(n) asm volatile("s_waitcnt vmcnt(" #n ")" ::: "memory")
; #define PG8_WAIT_L(n) asm volatile("s_waitcnt lgkmcnt(" #n ")" ::: "memory")
; #define PG8_BAR __builtin_amdgcn_s_barrier()
; #define PG8_SCHED __builtin_amdgcn_sched_barrier(0)
; template <class Epi, class Sched, bool ALIGN_EPI = false, bool SP2 = false>
; __device__ __forceinline__ void gemm_phase(PG8_LAS unsigned char* lds, const Gemm g, const Sched& S, const Epi& E) {
;     ...
;             PG8_LDA(At, 1, 1); PG8_STAGE(PG8_SB(1, 0), b3, voffB); PG8_STAGE(PG8_SB(1, 1), b3 + hstep, voffB); PG8_STAGE(PG8_SA(1, 0), a3, voffA);
;             PG8_WAIT_V(8); PG8_WAIT_L(0); PG8_BAR; PG8_MMA(1, 0, At, B0); PG8_MMA(1, 1, At, B1); PG8_BAR; PG8_SCHED;
	s_add_i32 s54, s79, s58
	v_lshl_add_u64 v[216:217], v[216:217], 0, s[18:19]
	s_mov_b32 m0, s54
	ds_read_b128 v[184:187], v157 offset:49152
	ds_read_b128 v[188:191], v157 offset:50176
	ds_read_b128 v[192:195], v157 offset:51200
	ds_read_b128 v[196:199], v157 offset:52224
	ds_read_b128 v[200:203], v157 offset:53248
	ds_read_b128 v[204:207], v157 offset:54272
	ds_read_b128 v[208:211], v157 offset:55296
	ds_read_b128 v[212:215], v157 offset:56320
	global_load_lds_dwordx4 v[216:217], off
	s_add_i32 m0, s54, 0x2000
	s_add_u32 s52, s52, 0x80080
	v_lshl_add_u64 v[216:217], v[220:221], 0, s[18:19]
	s_addc_u32 s53, s53, 0
	s_add_i32 s54, s80, s58
	global_load_lds_dwordx4 v[216:217], off
	v_lshl_add_u64 v[216:217], s[52:53], 0, v[132:133]
	s_mov_b32 m0, s54
	s_nop 0
	global_load_lds_dwordx4 v[216:217], off
	v_lshl_add_u64 v[216:217], s[52:53], 0, v[128:129]
	s_add_i32 m0, s54, 0x2000
	s_nop 0
	global_load_lds_dwordx4 v[216:217], off
	v_lshl_add_u64 v[216:217], v[222:223], 0, s[18:19]
	s_mov_b32 m0, s64
	s_nop 0
	global_load_lds_dwordx4 v[216:217], off
	v_lshl_add_u64 v[216:217], v[224:225], 0, s[18:19]
	s_mov_b32 m0, s65
	s_nop 0
	global_load_lds_dwordx4 v[216:217], off
	s_waitcnt vmcnt(8)
	s_waitcnt lgkmcnt(0)
	s_barrier
	s_setprio 1
	s_waitcnt lgkmcnt(0)
	v_mfma_f32_16x16x32_bf16 v[60:63], v[144:147], v[184:187], v[60:63]
	v_mfma_f32_16x16x32_bf16 v[56:59], v[160:163], v[184:187], v[56:59]
	v_mfma_f32_16x16x32_bf16 v[44:47], v[144:147], v[192:195], v[44:47]
	v_mfma_f32_16x16x32_bf16 v[40:43], v[160:163], v[192:195], v[40:43]
	v_mfma_f32_16x16x32_bf16 v[28:31], v[144:147], v[200:203], v[28:31]
	v_mfma_f32_16x16x32_bf16 v[24:27], v[160:163], v[200:203], v[24:27]
	v_mfma_f32_16x16x32_bf16 v[12:15], v[144:147], v[208:211], v[12:15]
	v_mfma_f32_16x16x32_bf16 v[8:11], v[160:163], v[208:211], v[8:11]
	v_mfma_f32_16x16x32_bf16 v[60:63], v[148:151], v[188:191], v[60:63]
	v_mfma_f32_16x16x32_bf16 v[56:59], v[164:167], v[188:191], v[56:59]
	v_mfma_f32_16x16x32_bf16 v[44:47], v[148:151], v[196:199], v[44:47]
	v_mfma_f32_16x16x32_bf16 v[40:43], v[164:167], v[196:199], v[40:43]
	v_mfma_f32_16x16x32_bf16 v[28:31], v[148:151], v[204:207], v[28:31]
	v_mfma_f32_16x16x32_bf16 v[24:27], v[164:167], v[204:207], v[24:27]
	v_mfma_f32_16x16x32_bf16 v[12:15], v[148:151], v[212:215], v[12:15]
	v_mfma_f32_16x16x32_bf16 v[8:11], v[164:167], v[212:215], v[8:11]
	s_setprio 0
	s_setprio 1
	v_mfma_f32_16x16x32_bf16 v[52:55], v[168:171], v[184:187], v[52:55]
	v_mfma_f32_16x16x32_bf16 v[48:51], v[176:179], v[184:187], v[48:51]
	v_mfma_f32_16x16x32_bf16 v[36:39], v[168:171], v[192:195], v[36:39]
	v_mfma_f32_16x16x32_bf16 v[32:35], v[176:179], v[192:195], v[32:35]
	v_mfma_f32_16x16x32_bf16 v[20:23], v[168:171], v[200:203], v[20:23]
	v_mfma_f32_16x16x32_bf16 v[16:19], v[176:179], v[200:203], v[16:19]
	v_mfma_f32_16x16x32_bf16 v[4:7], v[168:171], v[208:211], v[4:7]
	v_mfma_f32_16x16x32_bf16 v[0:3], v[176:179], v[208:211], v[0:3]
	v_mfma_f32_16x16x32_bf16 v[52:55], v[172:175], v[188:191], v[52:55]
	v_mfma_f32_16x16x32_bf16 v[48:51], v[180:183], v[188:191], v[48:51]
	v_mfma_f32_16x16x32_bf16 v[36:39], v[172:175], v[196:199], v[36:39]
	v_mfma_f32_16x16x32_bf16 v[32:35], v[180:183], v[196:199], v[32:35]
	v_mfma_f32_16x16x32_bf16 v[20:23], v[172:175], v[204:207], v[20:23]
	v_mfma_f32_16x16x32_bf16 v[16:19], v[180:183], v[204:207], v[16:19]
	v_mfma_f32_16x16x32_bf16 v[4:7], v[172:175], v[212:215], v[4:7]
	v_mfma_f32_16x16x32_bf16 v[0:3], v[180:183], v[212:215], v[0:3]
	s_setprio 0
	s_barrier
	s_add_i32 s78, s78, 2
	s_add_u32 s50, s50, 0x100
	s_addc_u32 s51, s51, 0
	s_add_u32 s76, s76, 0x100
	s_addc_u32 s77, s77, 0

; #define PG8_STAGE(bufoff, gbase, voff) do { _Pragma("unroll") for (int _i = 0; _i < 2; ++_i) \
;         __builtin_amdgcn_global_load_lds((const unsigned*)((const char*)(gbase) + (voff)[_i]), (PG8_LAS unsigned*)(lds + (bufoff) + ldsw + _i * 8192), 16, 0, 0); } while (0)
; #define PG8_LDA(dst, b, h) do { _Pragma("unroll") for (int m = 0; m < 4; ++m) _Pragma("unroll") for (int k = 0; k < 2; ++k) dst[m][k] = *(const PG8_LAS bf16x8*)(lds + PG8_SA(b, h) + aoff + m * 2048 + k * 1024); } while (0)
; #define PG8_LDB(dst, b, h) do { _Pragma("unroll") for (int n = 0; n < 2; ++n) _Pragma("unroll") for (int k = 0; k < 2; ++k) dst[n][k] = *(const PG8_LAS bf16x8*)(lds + PG8_SB(b, h) + boff + n * 2048 + k * 1024); } while (0)
; #define PG8_MMA(ai, bj, At, Bt) do { __builtin_amdgcn_s_setprio(1); _Pragma("unroll") for (int m = 0; m < 4; ++m) _Pragma("unroll") for (int n = 0; n < 2; ++n) _Pragma("unroll") for (int k = 0; k < 2; ++k) \
;         acc[ai][bj][m][n] = __builtin_amdgcn_mfma_f32_16x16x32_bf16(Bt[n][k], At[m][k], acc[ai][bj][m][n], 0, 0, 0); __builtin_amdgcn_s_setprio(0); } while (0)
; #define PG8_WAIT_V(n) asm volatile("s_waitcnt vmcnt(" #n ")" ::: "memory")
; #define PG8_WAIT_L(n) asm volatile("s_waitcnt lgkmcnt(" #n ")" ::: "memory")
; #define PG8_BAR __builtin_amdgcn_s_barrier()
; template <class Epi, class Sched, bool ALIGN_EPI = false, bool SP2 = false>
; __device__ __forceinline__ void gemm_phase(PG8_LAS unsigned char* lds, const Gemm g, const Sched& S, const Epi& E) {
;     ...
;             const char* a2 = last ? nA : cA + (size_t)(t + 2) * kstep; const char* b2 = last ? nB : cB + (size_t)(t + 2) * kstep;
;             const char* a3 = a2 + kstep; const char* b3 = b2 + kstep;
;             if (last && has_next) S.a_ready(nxt);
;             if constexpr (SP2) {
;             PG8_LDB(B0, 0, 0); PG8_LDB(B1, 0, 1); PG8_SCHED; PG8_LDA(At, 0, 0); PG8_STAGE(PG8_SA(1, 1), a1 + hstep, voffA);
;             PG8_WAIT_V(8); PG8_WAIT_L(0); PG8_BAR; PG8_MMA(0, 0, At, B0); PG8_MMA(0, 1, At, B1); PG8_BAR; PG8_SCHED;
;     ...
;         for (int a = 0; a < 2; ++a)
; #pragma unroll
;             for (int b = 0; b < 2; ++b)
; #pragma unroll
;                 for (int m = 0; m < 4; ++m)
; #pragma unroll
;                     for (int n = 0; n < 2; ++n) acc[a][b][m][n] = (f32x4){0.f, 0.f, 0.f, 0.f};
;         cur = nxt; cA = nA; cB = nB; ++ui;
.LBB0_1019:
	s_ashr_i32 s35, s34, 31
	s_lshl_b64 s[28:29], s[34:35], 20
	s_add_u32 s36, s46, s28
	s_addc_u32 s37, s47, s29
	s_and_b64 s[28:29], s[2:3], exec
	s_cselect_b32 s28, s37, s41
	s_cselect_b32 s29, s36, s40
	s_ashr_i32 s31, s30, 31
	s_lshl_b64 s[38:39], s[30:31], 20
	s_add_u32 s38, s48, s38
	s_addc_u32 s39, s49, s39
	s_and_b64 s[44:45], s[2:3], exec
	s_cselect_b32 s31, s39, s43
	s_cselect_b32 s35, s38, s42
	s_add_u32 s40, s40, 0x80080
	s_addc_u32 s41, s41, 0
	s_add_u32 s65, s42, 0x100
	v_mov_b32_e32 v0, 0
	s_addc_u32 s66, s43, 0
	s_mov_b32 s67, -2
	v_mov_b32_e32 v1, v0
	v_mov_b32_e32 v2, v0
	v_mov_b32_e32 v3, v0
	v_mov_b32_e32 v4, v0
	v_mov_b32_e32 v5, v0
	v_mov_b32_e32 v6, v0
	v_mov_b32_e32 v7, v0
	v_mov_b32_e32 v16, v0
	v_mov_b32_e32 v17, v0
	v_mov_b32_e32 v18, v0
	v_mov_b32_e32 v19, v0
	v_mov_b32_e32 v20, v0
	v_mov_b32_e32 v21, v0
	v_mov_b32_e32 v22, v0
	v_mov_b32_e32 v23, v0
	v_mov_b32_e32 v32, v0
	v_mov_b32_e32 v33, v0
	v_mov_b32_e32 v34, v0
	v_mov_b32_e32 v35, v0
	v_mov_b32_e32 v36, v0
	v_mov_b32_e32 v37, v0
	v_mov_b32_e32 v38, v0
	v_mov_b32_e32 v39, v0
	v_mov_b32_e32 v48, v0
	v_mov_b32_e32 v49, v0
	v_mov_b32_e32 v50, v0
	v_mov_b32_e32 v51, v0
	v_mov_b32_e32 v52, v0
	v_mov_b32_e32 v53, v0
	v_mov_b32_e32 v54, v0
	v_mov_b32_e32 v55, v0
	v_mov_b32_e32 v8, v0
	v_mov_b32_e32 v9, v0
	v_mov_b32_e32 v10, v0
	v_mov_b32_e32 v11, v0
	v_mov_b32_e32 v12, v0
	v_mov_b32_e32 v13, v0
	v_mov_b32_e32 v14, v0
	v_mov_b32_e32 v15, v0
	v_mov_b32_e32 v24, v0
	v_mov_b32_e32 v25, v0
	v_mov_b32_e32 v26, v0
	v_mov_b32_e32 v27, v0
	v_mov_b32_e32 v28, v0
	v_mov_b32_e32 v29, v0
	v_mov_b32_e32 v30, v0
	v_mov_b32_e32 v31, v0
	v_mov_b32_e32 v40, v0
	v_mov_b32_e32 v41, v0
	v_mov_b32_e32 v42, v0
	v_mov_b32_e32 v43, v0
	v_mov_b32_e32 v44, v0
	v_mov_b32_e32 v45, v0
	v_mov_b32_e32 v46, v0
	v_mov_b32_e32 v47, v0
	v_mov_b32_e32 v56, v0
	v_mov_b32_e32 v57, v0
	v_mov_b32_e32 v58, v0
	v_mov_b32_e32 v59, v0
	v_mov_b32_e32 v60, v0
	v_mov_b32_e32 v61, v0
	v_mov_b32_e32 v62, v0
	v_mov_b32_e32 v63, v0
	v_mov_b32_e32 v64, v0
	v_mov_b32_e32 v65, v0
	v_mov_b32_e32 v66, v0
	v_mov_b32_e32 v67, v0
	v_mov_b32_e32 v68, v0
	v_mov_b32_e32 v69, v0
	v_mov_b32_e32 v70, v0
	v_mov_b32_e32 v71, v0
	v_mov_b32_e32 v80, v0
	v_mov_b32_e32 v81, v0
	v_mov_b32_e32 v82, v0
	v_mov_b32_e32 v83, v0
	v_mov_b32_e32 v84, v0
	v_mov_b32_e32 v85, v0
	v_mov_b32_e32 v86, v0
	v_mov_b32_e32 v87, v0
	v_mov_b32_e32 v96, v0
	v_mov_b32_e32 v97, v0
	v_mov_b32_e32 v98, v0
	v_mov_b32_e32 v99, v0
	v_mov_b32_e32 v100, v0
	v_mov_b32_e32 v101, v0
	v_mov_b32_e32 v102, v0
	v_mov_b32_e32 v103, v0
	v_mov_b32_e32 v112, v0
	v_mov_b32_e32 v113, v0
	v_mov_b32_e32 v114, v0
	v_mov_b32_e32 v115, v0
	v_mov_b32_e32 v116, v0
	v_mov_b32_e32 v117, v0
	v_mov_b32_e32 v118, v0
	v_mov_b32_e32 v119, v0
	v_mov_b32_e32 v72, v0
	v_mov_b32_e32 v73, v0
	v_mov_b32_e32 v74, v0
	v_mov_b32_e32 v75, v0
	v_mov_b32_e32 v76, v0
	v_mov_b32_e32 v77, v0
	v_mov_b32_e32 v78, v0
	v_mov_b32_e32 v79, v0
	v_mov_b32_e32 v88, v0
	v_mov_b32_e32 v89, v0
	v_mov_b32_e32 v90, v0
	v_mov_b32_e32 v91, v0
	v_mov_b32_e32 v92, v0
	v_mov_b32_e32 v93, v0
	v_mov_b32_e32 v94, v0
	v_mov_b32_e32 v95, v0
	v_mov_b32_e32 v104, v0
	v_mov_b32_e32 v105, v0
	v_mov_b32_e32 v106, v0
	v_mov_b32_e32 v107, v0
	v_mov_b32_e32 v108, v0
	v_mov_b32_e32 v109, v0
	v_mov_b32_e32 v110, v0
	v_mov_b32_e32 v111, v0
	v_mov_b32_e32 v120, v0
	v_mov_b32_e32 v121, v0
	v_mov_b32_e32 v122, v0
	v_mov_b32_e32 v123, v0
	v_mov_b32_e32 v124, v0
	v_mov_b32_e32 v125, v0
	v_mov_b32_e32 v126, v0
	v_mov_b32_e32 v127, v0
	s_cmp_eq_u32 s57, 1
	s_cbranch_scc1 .LBB0_1020
	ds_read_b128 v[144:147], v155
	ds_read_b128 v[148:151], v155 offset:1024
	ds_read_b128 v[160:163], v155 offset:2048
	ds_read_b128 v[164:167], v155 offset:3072
	ds_read_b128 v[168:171], v156
	ds_read_b128 v[172:175], v156 offset:1024
	ds_read_b128 v[176:179], v156 offset:2048
	ds_read_b128 v[180:183], v156 offset:3072
	s_add_u32 s42, s40, 0xfff80080
	s_addc_u32 s43, s41, -1
	s_cmp_eq_u32 s67, 28
	s_cselect_b32 s45, s28, s43
	s_cselect_b32 s44, s29, s42
	s_cselect_b32 s43, s31, s66
	s_cselect_b32 s42, s35, s65
	v_lshl_add_u64 v[216:217], s[40:41], 0, v[136:137]
	s_add_i32 m0, s53, 0xc000
	ds_read_b128 v[184:187], v157
	ds_read_b128 v[188:191], v157 offset:1024
	ds_read_b128 v[192:195], v157 offset:2048
	ds_read_b128 v[196:199], v157 offset:3072
	ds_read_b128 v[200:203], v157 offset:4096
	ds_read_b128 v[204:207], v157 offset:5120
	ds_read_b128 v[208:211], v157 offset:6144
	ds_read_b128 v[212:215], v157 offset:7168
	global_load_lds_dwordx4 v[216:217], off
	v_lshl_add_u64 v[216:217], s[40:41], 0, v[138:139]
	s_add_i32 m0, s53, 0xe000
	s_nop 0
	global_load_lds_dwordx4 v[216:217], off
	s_waitcnt vmcnt(16)
	s_waitcnt lgkmcnt(0)
	s_barrier
; #define PG8_STAGE(bufoff, gbase, voff) do { _Pragma("unroll") for (int _i = 0; _i < 2; ++_i) \
;         __builtin_amdgcn_global_load_lds((const unsigned*)((const char*)(gbase) + (voff)[_i]), (PG8_LAS unsigned*)(lds + (bufoff) + ldsw + _i * 8192), 16, 0, 0); } while (0)
; #define PG8_LDA(dst, b, h) do { _Pragma("unroll") for (int m = 0; m < 4; ++m) _Pragma("unroll") for (int k = 0; k < 2; ++k) dst[m][k] = *(const PG8_LAS bf16x8*)(lds + PG8_SA(b, h) + aoff + m * 2048 + k * 1024); } while (0)
; #define PG8_MMA(ai, bj, At, Bt) do { __builtin_amdgcn_s_setprio(1); _Pragma("unroll") for (int m = 0; m < 4; ++m) _Pragma("unroll") for (int n = 0; n < 2; ++n) _Pragma("unroll") for (int k = 0; k < 2; ++k) \
;         acc[ai][bj][m][n] = __builtin_amdgcn_mfma_f32_16x16x32_bf16(Bt[n][k], At[m][k], acc[ai][bj][m][n], 0, 0, 0); __builtin_amdgcn_s_setprio(0); } while (0)
; #define PG8_WAIT_V(n) asm volatile("s_waitcnt vmcnt(" #n ")" ::: "memory")
; #define PG8_WAIT_L(n) asm volatile("s_waitcnt lgkmcnt(" #n ")" ::: "memory")
; #define PG8_BAR __builtin_amdgcn_s_barrier()
; #define PG8_SCHED __builtin_amdgcn_sched_barrier(0)
; template <class Epi, class Sched, bool ALIGN_EPI = false, bool SP2 = false>
; __device__ __forceinline__ void gemm_phase(PG8_LAS unsigned char* lds, const Gemm g, const Sched& S, const Epi& E) {
;     ...
;             PG8_WAIT_V(8); PG8_WAIT_L(0); PG8_BAR; PG8_MMA(0, 0, At, B0); PG8_MMA(0, 1, At, B1); PG8_BAR; PG8_SCHED;
;             PG8_LDA(At, 0, 1); PG8_STAGE(PG8_SB(0, 0), b2, voffB); PG8_STAGE(PG8_SB(0, 1), b2 + hstep, voffB); PG8_STAGE(PG8_SA(0, 0), a2, voffA);
;             PG8_WAIT_V(8); PG8_WAIT_L(0); PG8_BAR; PG8_MMA(1, 0, At, B0); PG8_MMA(1, 1, At, B1); PG8_BAR; PG8_SCHED;
	s_setprio 1
	s_waitcnt lgkmcnt(0)
	v_mfma_f32_16x16x32_bf16 v[124:127], v[144:147], v[184:187], v[124:127]
	v_mfma_f32_16x16x32_bf16 v[120:123], v[160:163], v[184:187], v[120:123]
	v_mfma_f32_16x16x32_bf16 v[108:111], v[144:147], v[192:195], v[108:111]
	v_mfma_f32_16x16x32_bf16 v[104:107], v[160:163], v[192:195], v[104:107]
	v_mfma_f32_16x16x32_bf16 v[92:95], v[144:147], v[200:203], v[92:95]
	v_mfma_f32_16x16x32_bf16 v[88:91], v[160:163], v[200:203], v[88:91]
	v_mfma_f32_16x16x32_bf16 v[76:79], v[144:147], v[208:211], v[76:79]
	v_mfma_f32_16x16x32_bf16 v[72:75], v[160:163], v[208:211], v[72:75]
	v_mfma_f32_16x16x32_bf16 v[124:127], v[148:151], v[188:191], v[124:127]
	v_mfma_f32_16x16x32_bf16 v[120:123], v[164:167], v[188:191], v[120:123]
	v_mfma_f32_16x16x32_bf16 v[108:111], v[148:151], v[196:199], v[108:111]
	v_mfma_f32_16x16x32_bf16 v[104:107], v[164:167], v[196:199], v[104:107]
	v_mfma_f32_16x16x32_bf16 v[92:95], v[148:151], v[204:207], v[92:95]
	v_mfma_f32_16x16x32_bf16 v[88:91], v[164:167], v[204:207], v[88:91]
	v_mfma_f32_16x16x32_bf16 v[76:79], v[148:151], v[212:215], v[76:79]
	v_mfma_f32_16x16x32_bf16 v[72:75], v[164:167], v[212:215], v[72:75]
	s_setprio 0
	s_setprio 1
	v_mfma_f32_16x16x32_bf16 v[116:119], v[168:171], v[184:187], v[116:119]
	v_mfma_f32_16x16x32_bf16 v[112:115], v[176:179], v[184:187], v[112:115]
	v_mfma_f32_16x16x32_bf16 v[100:103], v[168:171], v[192:195], v[100:103]
	v_mfma_f32_16x16x32_bf16 v[96:99], v[176:179], v[192:195], v[96:99]
	v_mfma_f32_16x16x32_bf16 v[84:87], v[168:171], v[200:203], v[84:87]
	v_mfma_f32_16x16x32_bf16 v[80:83], v[176:179], v[200:203], v[80:83]
	v_mfma_f32_16x16x32_bf16 v[68:71], v[168:171], v[208:211], v[68:71]
	v_mfma_f32_16x16x32_bf16 v[64:67], v[176:179], v[208:211], v[64:67]
	v_mfma_f32_16x16x32_bf16 v[116:119], v[172:175], v[188:191], v[116:119]
	v_mfma_f32_16x16x32_bf16 v[112:115], v[180:183], v[188:191], v[112:115]
	v_mfma_f32_16x16x32_bf16 v[100:103], v[172:175], v[196:199], v[100:103]
	v_mfma_f32_16x16x32_bf16 v[96:99], v[180:183], v[196:199], v[96:99]
	v_mfma_f32_16x16x32_bf16 v[84:87], v[172:175], v[204:207], v[84:87]
	v_mfma_f32_16x16x32_bf16 v[80:83], v[180:183], v[204:207], v[80:83]
	v_mfma_f32_16x16x32_bf16 v[68:71], v[172:175], v[212:215], v[68:71]
	v_mfma_f32_16x16x32_bf16 v[64:67], v[180:183], v[212:215], v[64:67]
	s_setprio 0
	s_barrier
	s_add_i32 s68, s61, s50
	v_lshl_add_u64 v[216:217], s[42:43], 0, v[132:133]
	s_mov_b32 m0, s68
	ds_read_b128 v[184:187], v157 offset:16384
	ds_read_b128 v[188:191], v157 offset:17408
	ds_read_b128 v[192:195], v157 offset:18432
	ds_read_b128 v[196:199], v157 offset:19456
	ds_read_b128 v[200:203], v157 offset:20480
	ds_read_b128 v[204:207], v157 offset:21504
	ds_read_b128 v[208:211], v157 offset:22528
	ds_read_b128 v[212:215], v157 offset:23552
	global_load_lds_dwordx4 v[216:217], off
	s_add_i32 m0, s68, 0x2000
	s_add_u32 s68, s42, 0x80000
	v_lshl_add_u64 v[220:221], s[42:43], 0, v[128:129]
	s_addc_u32 s69, s43, 0
	s_add_i32 s70, s62, s50
	global_load_lds_dwordx4 v[220:221], off
	v_lshl_add_u64 v[222:223], s[68:69], 0, v[132:133]
	s_mov_b32 m0, s70
	v_lshl_add_u64 v[224:225], s[44:45], 0, v[130:131]
	global_load_lds_dwordx4 v[222:223], off
	v_lshl_add_u64 v[222:223], s[68:69], 0, v[128:129]
	s_add_i32 m0, s70, 0x2000
	s_nop 0
	global_load_lds_dwordx4 v[222:223], off
	v_lshl_add_u64 v[222:223], s[44:45], 0, v[134:135]
	s_mov_b32 m0, s53
	s_nop 0
	global_load_lds_dwordx4 v[222:223], off
	s_mov_b32 m0, s54
	s_nop 0
	global_load_lds_dwordx4 v[224:225], off
	s_waitcnt vmcnt(16)
	s_waitcnt lgkmcnt(0)
	s_barrier
	s_setprio 1
	s_waitcnt lgkmcnt(0)
	v_mfma_f32_16x16x32_bf16 v[60:63], v[144:147], v[184:187], v[60:63]
	v_mfma_f32_16x16x32_bf16 v[56:59], v[160:163], v[184:187], v[56:59]
	v_mfma_f32_16x16x32_bf16 v[44:47], v[144:147], v[192:195], v[44:47]
	v_mfma_f32_16x16x32_bf16 v[40:43], v[160:163], v[192:195], v[40:43]
	v_mfma_f32_16x16x32_bf16 v[28:31], v[144:147], v[200:203], v[28:31]
	v_mfma_f32_16x16x32_bf16 v[24:27], v[160:163], v[200:203], v[24:27]
	v_mfma_f32_16x16x32_bf16 v[12:15], v[144:147], v[208:211], v[12:15]
	v_mfma_f32_16x16x32_bf16 v[8:11], v[160:163], v[208:211], v[8:11]
	v_mfma_f32_16x16x32_bf16 v[60:63], v[148:151], v[188:191], v[60:63]
	v_mfma_f32_16x16x32_bf16 v[56:59], v[164:167], v[188:191], v[56:59]
	v_mfma_f32_16x16x32_bf16 v[44:47], v[148:151], v[196:199], v[44:47]
	v_mfma_f32_16x16x32_bf16 v[40:43], v[164:167], v[196:199], v[40:43]
	v_mfma_f32_16x16x32_bf16 v[28:31], v[148:151], v[204:207], v[28:31]
	v_mfma_f32_16x16x32_bf16 v[24:27], v[164:167], v[204:207], v[24:27]
	v_mfma_f32_16x16x32_bf16 v[12:15], v[148:151], v[212:215], v[12:15]
	v_mfma_f32_16x16x32_bf16 v[8:11], v[164:167], v[212:215], v[8:11]
	s_setprio 0
	s_setprio 1
	v_mfma_f32_16x16x32_bf16 v[52:55], v[168:171], v[184:187], v[52:55]
	v_mfma_f32_16x16x32_bf16 v[48:51], v[176:179], v[184:187], v[48:51]
	v_mfma_f32_16x16x32_bf16 v[36:39], v[168:171], v[192:195], v[36:39]
	v_mfma_f32_16x16x32_bf16 v[32:35], v[176:179], v[192:195], v[32:35]
	v_mfma_f32_16x16x32_bf16 v[20:23], v[168:171], v[200:203], v[20:23]
	v_mfma_f32_16x16x32_bf16 v[16:19], v[176:179], v[200:203], v[16:19]
	v_mfma_f32_16x16x32_bf16 v[4:7], v[168:171], v[208:211], v[4:7]
	v_mfma_f32_16x16x32_bf16 v[0:3], v[176:179], v[208:211], v[0:3]
	v_mfma_f32_16x16x32_bf16 v[52:55], v[172:175], v[188:191], v[52:55]
	v_mfma_f32_16x16x32_bf16 v[48:51], v[180:183], v[188:191], v[48:51]
	v_mfma_f32_16x16x32_bf16 v[36:39], v[172:175], v[196:199], v[36:39]
	v_mfma_f32_16x16x32_bf16 v[32:35], v[180:183], v[196:199], v[32:35]
	v_mfma_f32_16x16x32_bf16 v[20:23], v[172:175], v[204:207], v[20:23]
	v_mfma_f32_16x16x32_bf16 v[16:19], v[180:183], v[204:207], v[16:19]
	v_mfma_f32_16x16x32_bf16 v[4:7], v[172:175], v[212:215], v[4:7]
	v_mfma_f32_16x16x32_bf16 v[0:3], v[180:183], v[212:215], v[0:3]
	s_setprio 0
	s_barrier
; #define PG8_STAGE(bufoff, gbase, voff) do { _Pragma("unroll") for (int _i = 0; _i < 2; ++_i) \
;         __builtin_amdgcn_global_load_lds((const unsigned*)((const char*)(gbase) + (voff)[_i]), (PG8_LAS unsigned*)(lds + (bufoff) + ldsw + _i * 8192), 16, 0, 0); } while (0)
; #define PG8_LDA(dst, b, h) do { _Pragma("unroll") for (int m = 0; m < 4; ++m) _Pragma("unroll") for (int k = 0; k < 2; ++k) dst[m][k] = *(const PG8_LAS bf16x8*)(lds + PG8_SA(b, h) + aoff + m * 2048 + k * 1024); } while (0)
; #define PG8_LDB(dst, b, h) do { _Pragma("unroll") for (int n = 0; n < 2; ++n) _Pragma("unroll") for (int k = 0; k < 2; ++k) dst[n][k] = *(const PG8_LAS bf16x8*)(lds + PG8_SB(b, h) + boff + n * 2048 + k * 1024); } while (0)
; #define PG8_MMA(ai, bj, At, Bt) do { __builtin_amdgcn_s_setprio(1); _Pragma("unroll") for (int m = 0; m < 4; ++m) _Pragma("unroll") for (int n = 0; n < 2; ++n) _Pragma("unroll") for (int k = 0; k < 2; ++k) \
;         acc[ai][bj][m][n] = __builtin_amdgcn_mfma_f32_16x16x32_bf16(Bt[n][k], At[m][k], acc[ai][bj][m][n], 0, 0, 0); __builtin_amdgcn_s_setprio(0); } while (0)
; #define PG8_WAIT_V(n) asm volatile("s_waitcnt vmcnt(" #n ")" ::: "memory")
; #define PG8_WAIT_L(n) asm volatile("s_waitcnt lgkmcnt(" #n ")" ::: "memory")
; #define PG8_BAR __builtin_amdgcn_s_barrier()
; #define PG8_SCHED __builtin_amdgcn_sched_barrier(0)
; template <class Epi, class Sched, bool ALIGN_EPI = false, bool SP2 = false>
; __device__ __forceinline__ void gemm_phase(PG8_LAS unsigned char* lds, const Gemm g, const Sched& S, const Epi& E) {
;     ...
;             PG8_LDB(B0, 1, 0); PG8_LDB(B1, 1, 1); PG8_SCHED; PG8_LDA(At, 1, 0); PG8_STAGE(PG8_SA(0, 1), a2 + hstep, voffA);
;             PG8_WAIT_V(8); PG8_WAIT_L(0); PG8_BAR; PG8_MMA(0, 0, At, B0); PG8_MMA(0, 1, At, B1); PG8_BAR; PG8_SCHED;
	s_add_i32 s68, 0, 0x18000
	s_add_i32 s69, 0, 0x1c000
	v_add_u32_e32 v164, s68, v153
	v_add_u32_e32 v180, s69, v153
	ds_read_b128 v[144:147], v164
	ds_read_b128 v[148:151], v164 offset:1024
	ds_read_b128 v[160:163], v164 offset:2048
	ds_read_b128 v[164:167], v164 offset:3072
	ds_read_b128 v[168:171], v180
	ds_read_b128 v[172:175], v180 offset:1024
	ds_read_b128 v[176:179], v180 offset:2048
	ds_read_b128 v[180:183], v180 offset:3072
	s_add_u32 s44, s44, 0x80000
	s_addc_u32 s45, s45, 0
	s_mov_b32 m0, s55
	v_lshl_add_u64 v[226:227], s[44:45], 0, v[134:135]
	ds_read_b128 v[184:187], v157 offset:32768
	ds_read_b128 v[188:191], v157 offset:33792
	ds_read_b128 v[192:195], v157 offset:34816
	ds_read_b128 v[196:199], v157 offset:35840
	ds_read_b128 v[200:203], v157 offset:36864
	ds_read_b128 v[204:207], v157 offset:37888
	ds_read_b128 v[208:211], v157 offset:38912
	ds_read_b128 v[212:215], v157 offset:39936
	global_load_lds_dwordx4 v[226:227], off
	v_lshl_add_u64 v[226:227], s[44:45], 0, v[130:131]
	s_mov_b32 m0, s56
	s_nop 0
	global_load_lds_dwordx4 v[226:227], off
	s_waitcnt vmcnt(8)
	s_waitcnt lgkmcnt(0)
	s_barrier
	s_setprio 1
	s_waitcnt lgkmcnt(0)
	v_mfma_f32_16x16x32_bf16 v[124:127], v[144:147], v[184:187], v[124:127]
	v_mfma_f32_16x16x32_bf16 v[120:123], v[160:163], v[184:187], v[120:123]
	v_mfma_f32_16x16x32_bf16 v[108:111], v[144:147], v[192:195], v[108:111]
	v_mfma_f32_16x16x32_bf16 v[104:107], v[160:163], v[192:195], v[104:107]
	v_mfma_f32_16x16x32_bf16 v[92:95], v[144:147], v[200:203], v[92:95]
	v_mfma_f32_16x16x32_bf16 v[88:91], v[160:163], v[200:203], v[88:91]
	v_mfma_f32_16x16x32_bf16 v[76:79], v[144:147], v[208:211], v[76:79]
	v_mfma_f32_16x16x32_bf16 v[72:75], v[160:163], v[208:211], v[72:75]
	v_mfma_f32_16x16x32_bf16 v[124:127], v[148:151], v[188:191], v[124:127]
	v_mfma_f32_16x16x32_bf16 v[120:123], v[164:167], v[188:191], v[120:123]
	v_mfma_f32_16x16x32_bf16 v[108:111], v[148:151], v[196:199], v[108:111]
	v_mfma_f32_16x16x32_bf16 v[104:107], v[164:167], v[196:199], v[104:107]
	v_mfma_f32_16x16x32_bf16 v[92:95], v[148:151], v[204:207], v[92:95]
	v_mfma_f32_16x16x32_bf16 v[88:91], v[164:167], v[204:207], v[88:91]
	v_mfma_f32_16x16x32_bf16 v[76:79], v[148:151], v[212:215], v[76:79]
	v_mfma_f32_16x16x32_bf16 v[72:75], v[164:167], v[212:215], v[72:75]
	s_setprio 0
	s_setprio 1
	v_mfma_f32_16x16x32_bf16 v[116:119], v[168:171], v[184:187], v[116:119]
	v_mfma_f32_16x16x32_bf16 v[112:115], v[176:179], v[184:187], v[112:115]
	v_mfma_f32_16x16x32_bf16 v[100:103], v[168:171], v[192:195], v[100:103]
	v_mfma_f32_16x16x32_bf16 v[96:99], v[176:179], v[192:195], v[96:99]
	v_mfma_f32_16x16x32_bf16 v[84:87], v[168:171], v[200:203], v[84:87]
	v_mfma_f32_16x16x32_bf16 v[80:83], v[176:179], v[200:203], v[80:83]
	v_mfma_f32_16x16x32_bf16 v[68:71], v[168:171], v[208:211], v[68:71]
	v_mfma_f32_16x16x32_bf16 v[64:67], v[176:179], v[208:211], v[64:67]
	v_mfma_f32_16x16x32_bf16 v[116:119], v[172:175], v[188:191], v[116:119]
	v_mfma_f32_16x16x32_bf16 v[112:115], v[180:183], v[188:191], v[112:115]
	v_mfma_f32_16x16x32_bf16 v[100:103], v[172:175], v[196:199], v[100:103]
	v_mfma_f32_16x16x32_bf16 v[96:99], v[180:183], v[196:199], v[96:99]
	v_mfma_f32_16x16x32_bf16 v[84:87], v[172:175], v[204:207], v[84:87]
	v_mfma_f32_16x16x32_bf16 v[80:83], v[180:183], v[204:207], v[80:83]
	v_mfma_f32_16x16x32_bf16 v[68:71], v[172:175], v[212:215], v[68:71]
	v_mfma_f32_16x16x32_bf16 v[64:67], v[180:183], v[212:215], v[64:67]
	s_setprio 0
	s_barrier
; #define PG8_STAGE(bufoff, gbase, voff) do { _Pragma("unroll") for (int _i = 0; _i < 2; ++_i) \
;         __builtin_amdgcn_global_load_lds((const unsigned*)((const char*)(gbase) + (voff)[_i]), (PG8_LAS unsigned*)(lds + (bufoff) + ldsw + _i * 8192), 16, 0, 0); } while (0)
; #define PG8_LDA(dst, b, h) do { _Pragma("unroll") for (int m = 0; m < 4; ++m) _Pragma("unroll") for (int k = 0; k < 2; ++k) dst[m][k] = *(const PG8_LAS bf16x8*)(lds + PG8_SA(b, h) + aoff + m * 2048 + k * 1024); } while (0)
; #define PG8_MMA(ai, bj, At, Bt) do { __builtin_amdgcn_s_setprio(1); _Pragma("unroll") for (int m = 0; m < 4; ++m) _Pragma("unroll") for (int n = 0; n < 2; ++n) _Pragma("unroll") for (int k = 0; k < 2; ++k) \
;         acc[ai][bj][m][n] = __builtin_amdgcn_mfma_f32_16x16x32_bf16(Bt[n][k], At[m][k], acc[ai][bj][m][n], 0, 0, 0); __builtin_amdgcn_s_setprio(0); } while (0)
; #define PG8_WAIT_V(n) asm volatile("s_waitcnt vmcnt(" #n ")" ::: "memory")
; #define PG8_WAIT_L(n) asm volatile("s_waitcnt lgkmcnt(" #n ")" ::: "memory")
; #define PG8_BAR __builtin_amdgcn_s_barrier()
; #define PG8_SCHED __builtin_amdgcn_sched_barrier(0)
; template <class Epi, class Sched, bool ALIGN_EPI = false, bool SP2 = false>
; __device__ __forceinline__ void gemm_phase(PG8_LAS unsigned char* lds, const Gemm g, const Sched& S, const Epi& E) {
;     ...
;             PG8_LDA(At, 1, 1); PG8_STAGE(PG8_SB(1, 0), b3, voffB); PG8_STAGE(PG8_SB(1, 1), b3 + hstep, voffB); PG8_STAGE(PG8_SA(1, 0), a3, voffA);
;             PG8_WAIT_V(8); PG8_WAIT_L(0); PG8_BAR; PG8_MMA(1, 0, At, B0); PG8_MMA(1, 1, At, B1); PG8_BAR; PG8_SCHED;
	s_add_i32 s44, s68, s50
	v_lshl_add_u64 v[216:217], v[216:217], 0, s[18:19]
	s_mov_b32 m0, s44
	ds_read_b128 v[184:187], v157 offset:49152
	ds_read_b128 v[188:191], v157 offset:50176
	ds_read_b128 v[192:195], v157 offset:51200
	ds_read_b128 v[196:199], v157 offset:52224
	ds_read_b128 v[200:203], v157 offset:53248
	ds_read_b128 v[204:207], v157 offset:54272
	ds_read_b128 v[208:211], v157 offset:55296
	ds_read_b128 v[212:215], v157 offset:56320
	global_load_lds_dwordx4 v[216:217], off
	s_add_i32 m0, s44, 0x2000
	s_add_u32 s42, s42, 0x80080
	v_lshl_add_u64 v[216:217], v[220:221], 0, s[18:19]
	s_addc_u32 s43, s43, 0
	s_add_i32 s44, s69, s50
	global_load_lds_dwordx4 v[216:217], off
	v_lshl_add_u64 v[216:217], s[42:43], 0, v[132:133]
	s_mov_b32 m0, s44
	s_nop 0
	global_load_lds_dwordx4 v[216:217], off
	v_lshl_add_u64 v[216:217], s[42:43], 0, v[128:129]
	s_add_i32 m0, s44, 0x2000
	s_nop 0
	global_load_lds_dwordx4 v[216:217], off
	v_lshl_add_u64 v[216:217], v[222:223], 0, s[18:19]
	s_mov_b32 m0, s58
	s_nop 0
	global_load_lds_dwordx4 v[216:217], off
	v_lshl_add_u64 v[216:217], v[224:225], 0, s[18:19]
	s_mov_b32 m0, s59
	s_nop 0
	global_load_lds_dwordx4 v[216:217], off
	s_waitcnt vmcnt(8)
	s_waitcnt lgkmcnt(0)
	s_barrier
	s_setprio 1
	s_waitcnt lgkmcnt(0)
	v_mfma_f32_16x16x32_bf16 v[60:63], v[144:147], v[184:187], v[60:63]
	v_mfma_f32_16x16x32_bf16 v[56:59], v[160:163], v[184:187], v[56:59]
	v_mfma_f32_16x16x32_bf16 v[44:47], v[144:147], v[192:195], v[44:47]
	v_mfma_f32_16x16x32_bf16 v[40:43], v[160:163], v[192:195], v[40:43]
	v_mfma_f32_16x16x32_bf16 v[28:31], v[144:147], v[200:203], v[28:31]
	v_mfma_f32_16x16x32_bf16 v[24:27], v[160:163], v[200:203], v[24:27]
	v_mfma_f32_16x16x32_bf16 v[12:15], v[144:147], v[208:211], v[12:15]
	v_mfma_f32_16x16x32_bf16 v[8:11], v[160:163], v[208:211], v[8:11]
	v_mfma_f32_16x16x32_bf16 v[60:63], v[148:151], v[188:191], v[60:63]
	v_mfma_f32_16x16x32_bf16 v[56:59], v[164:167], v[188:191], v[56:59]
	v_mfma_f32_16x16x32_bf16 v[44:47], v[148:151], v[196:199], v[44:47]
	v_mfma_f32_16x16x32_bf16 v[40:43], v[164:167], v[196:199], v[40:43]
	v_mfma_f32_16x16x32_bf16 v[28:31], v[148:151], v[204:207], v[28:31]
	v_mfma_f32_16x16x32_bf16 v[24:27], v[164:167], v[204:207], v[24:27]
	v_mfma_f32_16x16x32_bf16 v[12:15], v[148:151], v[212:215], v[12:15]
	v_mfma_f32_16x16x32_bf16 v[8:11], v[164:167], v[212:215], v[8:11]
	s_setprio 0
	s_setprio 1
	v_mfma_f32_16x16x32_bf16 v[52:55], v[168:171], v[184:187], v[52:55]
	v_mfma_f32_16x16x32_bf16 v[48:51], v[176:179], v[184:187], v[48:51]
	v_mfma_f32_16x16x32_bf16 v[36:39], v[168:171], v[192:195], v[36:39]
	v_mfma_f32_16x16x32_bf16 v[32:35], v[176:179], v[192:195], v[32:35]
	v_mfma_f32_16x16x32_bf16 v[20:23], v[168:171], v[200:203], v[20:23]
	v_mfma_f32_16x16x32_bf16 v[16:19], v[176:179], v[200:203], v[16:19]
	v_mfma_f32_16x16x32_bf16 v[4:7], v[168:171], v[208:211], v[4:7]
	v_mfma_f32_16x16x32_bf16 v[0:3], v[176:179], v[208:211], v[0:3]
	v_mfma_f32_16x16x32_bf16 v[52:55], v[172:175], v[188:191], v[52:55]
	v_mfma_f32_16x16x32_bf16 v[48:51], v[180:183], v[188:191], v[48:51]
	v_mfma_f32_16x16x32_bf16 v[36:39], v[172:175], v[196:199], v[36:39]
	v_mfma_f32_16x16x32_bf16 v[32:35], v[180:183], v[196:199], v[32:35]
	v_mfma_f32_16x16x32_bf16 v[20:23], v[172:175], v[204:207], v[20:23]
	v_mfma_f32_16x16x32_bf16 v[16:19], v[180:183], v[204:207], v[16:19]
	v_mfma_f32_16x16x32_bf16 v[4:7], v[172:175], v[212:215], v[4:7]
	v_mfma_f32_16x16x32_bf16 v[0:3], v[180:183], v[212:215], v[0:3]
	s_setprio 0
	s_barrier
	s_add_i32 s67, s67, 2
	s_add_u32 s40, s40, 0x100
	s_addc_u32 s41, s41, 0
	s_add_u32 s65, s65, 0x100
	s_addc_u32 s66, s66, 0
